# v28 + vmcnt(8) and lgkmcnt(0) waits of the K-loop load segments merged into one instruction, no-op setprio 0/3 pairs removed
# speedup vs baseline: 1.0007x; 1.0007x over previous
.LBB0_134:
	s_add_u32 s0, s34, 0xfff00080
	s_addc_u32 s1, s35, -1
	s_cmp_eq_u32 s60, 60
	s_cselect_b32 s39, s12, s1
	s_cselect_b32 s38, s13, s0
	s_cselect_b32 s37, s15, s59
	s_cselect_b32 s36, s57, s58
	s_add_i32 m0, s29, 0xc000
	ds_read_b128 v[148:151], v156
	global_load_lds_dwordx4 v140, s[34:35]
	s_add_i32 m0, s29, 0xe000
	ds_read_b128 v[160:163], v156 offset:1024
	global_load_lds_dwordx4 v142, s[34:35]
	ds_read_b128 v[164:167], v156 offset:2048
	ds_read_b128 v[168:171], v156 offset:3072
	ds_read_b128 v[172:175], v157
	ds_read_b128 v[176:179], v157 offset:1024
	ds_read_b128 v[180:183], v157 offset:2048
	ds_read_b128 v[184:187], v157 offset:3072
	ds_read_b128 v[188:191], v158
	ds_read_b128 v[192:195], v158 offset:1024
	ds_read_b128 v[196:199], v158 offset:2048
	ds_read_b128 v[200:203], v158 offset:3072
	ds_read_b128 v[208:211], v158 offset:4096
	ds_read_b128 v[212:215], v158 offset:5120
	ds_read_b128 v[216:219], v158 offset:6144
	ds_read_b128 v[220:223], v158 offset:7168
	s_waitcnt vmcnt(8) lgkmcnt(0)
	s_setprio 3
	s_barrier
	v_mfma_f32_16x16x32_bf16 v[124:127], v[148:151], v[188:191], v[124:127]
	v_mfma_f32_16x16x32_bf16 v[120:123], v[164:167], v[188:191], v[120:123]
	v_mfma_f32_16x16x32_bf16 v[108:111], v[148:151], v[196:199], v[108:111]
	v_mfma_f32_16x16x32_bf16 v[104:107], v[164:167], v[196:199], v[104:107]
	v_mfma_f32_16x16x32_bf16 v[92:95], v[148:151], v[208:211], v[92:95]
	v_mfma_f32_16x16x32_bf16 v[88:91], v[164:167], v[208:211], v[88:91]
	v_mfma_f32_16x16x32_bf16 v[76:79], v[148:151], v[216:219], v[76:79]
	v_mfma_f32_16x16x32_bf16 v[72:75], v[164:167], v[216:219], v[72:75]
	v_mfma_f32_16x16x32_bf16 v[124:127], v[160:163], v[192:195], v[124:127]
	v_mfma_f32_16x16x32_bf16 v[120:123], v[168:171], v[192:195], v[120:123]
	v_mfma_f32_16x16x32_bf16 v[108:111], v[160:163], v[200:203], v[108:111]
	v_mfma_f32_16x16x32_bf16 v[104:107], v[168:171], v[200:203], v[104:107]
	v_mfma_f32_16x16x32_bf16 v[92:95], v[160:163], v[212:215], v[92:95]
	v_mfma_f32_16x16x32_bf16 v[88:91], v[168:171], v[212:215], v[88:91]
	v_mfma_f32_16x16x32_bf16 v[76:79], v[160:163], v[220:223], v[76:79]
	v_mfma_f32_16x16x32_bf16 v[72:75], v[168:171], v[220:223], v[72:75]
	v_mfma_f32_16x16x32_bf16 v[116:119], v[172:175], v[188:191], v[116:119]
	v_mfma_f32_16x16x32_bf16 v[112:115], v[180:183], v[188:191], v[112:115]
	v_mfma_f32_16x16x32_bf16 v[100:103], v[172:175], v[196:199], v[100:103]
	v_mfma_f32_16x16x32_bf16 v[96:99], v[180:183], v[196:199], v[96:99]
	v_mfma_f32_16x16x32_bf16 v[84:87], v[172:175], v[208:211], v[84:87]
	v_mfma_f32_16x16x32_bf16 v[80:83], v[180:183], v[208:211], v[80:83]
	v_mfma_f32_16x16x32_bf16 v[68:71], v[172:175], v[216:219], v[68:71]
	v_mfma_f32_16x16x32_bf16 v[64:67], v[180:183], v[216:219], v[64:67]
	v_mfma_f32_16x16x32_bf16 v[116:119], v[176:179], v[192:195], v[116:119]
	v_mfma_f32_16x16x32_bf16 v[112:115], v[184:187], v[192:195], v[112:115]
	v_mfma_f32_16x16x32_bf16 v[100:103], v[176:179], v[200:203], v[100:103]
	v_mfma_f32_16x16x32_bf16 v[96:99], v[184:187], v[200:203], v[96:99]
	v_mfma_f32_16x16x32_bf16 v[84:87], v[176:179], v[212:215], v[84:87]
	v_mfma_f32_16x16x32_bf16 v[80:83], v[184:187], v[212:215], v[80:83]
	v_mfma_f32_16x16x32_bf16 v[68:71], v[176:179], v[220:223], v[68:71]
	v_mfma_f32_16x16x32_bf16 v[64:67], v[184:187], v[220:223], v[64:67]
	s_barrier
	s_setprio 0
	s_add_i32 s0, s51, s41
	s_mov_b32 m0, s0
	ds_read_b128 v[188:191], v158 offset:16384
	global_load_lds_dwordx4 v132, s[36:37]
	s_add_i32 m0, s0, 0x2000
	ds_read_b128 v[192:195], v158 offset:17408
	global_load_lds_dwordx4 v136, s[36:37]
	s_add_u32 s62, s36, 0x100000
	s_addc_u32 s63, s37, 0
	s_add_i32 s0, s52, s41
	s_mov_b32 m0, s0
	ds_read_b128 v[196:199], v158 offset:18432
	global_load_lds_dwordx4 v132, s[62:63]
	s_add_i32 m0, s0, 0x2000
	ds_read_b128 v[200:203], v158 offset:19456
	global_load_lds_dwordx4 v136, s[62:63]
	s_mov_b32 m0, s29
	ds_read_b128 v[208:211], v158 offset:20480
	global_load_lds_dwordx4 v130, s[38:39]
	s_mov_b32 m0, s31
	ds_read_b128 v[212:215], v158 offset:21504
	global_load_lds_dwordx4 v134, s[38:39]
	ds_read_b128 v[216:219], v158 offset:22528
	ds_read_b128 v[220:223], v158 offset:23552
	s_waitcnt vmcnt(8) lgkmcnt(0)
	s_setprio 3
	s_barrier
	v_mfma_f32_16x16x32_bf16 v[60:63], v[148:151], v[188:191], v[60:63]
	v_mfma_f32_16x16x32_bf16 v[56:59], v[164:167], v[188:191], v[56:59]
	v_mfma_f32_16x16x32_bf16 v[44:47], v[148:151], v[196:199], v[44:47]
	v_mfma_f32_16x16x32_bf16 v[40:43], v[164:167], v[196:199], v[40:43]
	v_mfma_f32_16x16x32_bf16 v[28:31], v[148:151], v[208:211], v[28:31]
	v_mfma_f32_16x16x32_bf16 v[24:27], v[164:167], v[208:211], v[24:27]
	v_mfma_f32_16x16x32_bf16 v[12:15], v[148:151], v[216:219], v[12:15]
	v_mfma_f32_16x16x32_bf16 v[8:11], v[164:167], v[216:219], v[8:11]
	v_mfma_f32_16x16x32_bf16 v[60:63], v[160:163], v[192:195], v[60:63]
	v_mfma_f32_16x16x32_bf16 v[56:59], v[168:171], v[192:195], v[56:59]
	v_mfma_f32_16x16x32_bf16 v[44:47], v[160:163], v[200:203], v[44:47]
	v_mfma_f32_16x16x32_bf16 v[40:43], v[168:171], v[200:203], v[40:43]
	v_mfma_f32_16x16x32_bf16 v[28:31], v[160:163], v[212:215], v[28:31]
	v_mfma_f32_16x16x32_bf16 v[24:27], v[168:171], v[212:215], v[24:27]
	v_mfma_f32_16x16x32_bf16 v[12:15], v[160:163], v[220:223], v[12:15]
	v_mfma_f32_16x16x32_bf16 v[8:11], v[168:171], v[220:223], v[8:11]
	v_mfma_f32_16x16x32_bf16 v[52:55], v[172:175], v[188:191], v[52:55]
	v_mfma_f32_16x16x32_bf16 v[48:51], v[180:183], v[188:191], v[48:51]
	v_mfma_f32_16x16x32_bf16 v[36:39], v[172:175], v[196:199], v[36:39]
	v_mfma_f32_16x16x32_bf16 v[32:35], v[180:183], v[196:199], v[32:35]
	v_mfma_f32_16x16x32_bf16 v[20:23], v[172:175], v[208:211], v[20:23]
	v_mfma_f32_16x16x32_bf16 v[16:19], v[180:183], v[208:211], v[16:19]
	v_mfma_f32_16x16x32_bf16 v[4:7], v[172:175], v[216:219], v[4:7]
	v_mfma_f32_16x16x32_bf16 v[0:3], v[180:183], v[216:219], v[0:3]
	v_mfma_f32_16x16x32_bf16 v[52:55], v[176:179], v[192:195], v[52:55]
	v_mfma_f32_16x16x32_bf16 v[48:51], v[184:187], v[192:195], v[48:51]
	v_mfma_f32_16x16x32_bf16 v[36:39], v[176:179], v[200:203], v[36:39]
	v_mfma_f32_16x16x32_bf16 v[32:35], v[184:187], v[200:203], v[32:35]
	v_mfma_f32_16x16x32_bf16 v[20:23], v[176:179], v[212:215], v[20:23]
	v_mfma_f32_16x16x32_bf16 v[16:19], v[184:187], v[212:215], v[16:19]
	v_mfma_f32_16x16x32_bf16 v[4:7], v[176:179], v[220:223], v[4:7]
	v_mfma_f32_16x16x32_bf16 v[0:3], v[184:187], v[220:223], v[0:3]
	s_barrier
	s_setprio 0
	s_add_i32 s0, 0, 0x18000
	s_add_i32 s1, 0, 0x1c000
	ds_read_b128 v[148:151], v228
	ds_read_b128 v[160:163], v228 offset:1024
	ds_read_b128 v[164:167], v228 offset:2048
	ds_read_b128 v[168:171], v228 offset:3072
	ds_read_b128 v[172:175], v229
	ds_read_b128 v[176:179], v229 offset:1024
	ds_read_b128 v[180:183], v229 offset:2048
	ds_read_b128 v[184:187], v229 offset:3072
	s_add_u32 s38, s38, 0x100000
	s_addc_u32 s39, s39, 0
	s_mov_b32 m0, s42
	ds_read_b128 v[188:191], v158 offset:32768
	global_load_lds_dwordx4 v130, s[38:39]
	s_mov_b32 m0, s43
	ds_read_b128 v[192:195], v158 offset:33792
	global_load_lds_dwordx4 v134, s[38:39]
	ds_read_b128 v[196:199], v158 offset:34816
	ds_read_b128 v[200:203], v158 offset:35840
	ds_read_b128 v[208:211], v158 offset:36864
	ds_read_b128 v[212:215], v158 offset:37888
	ds_read_b128 v[216:219], v158 offset:38912
	ds_read_b128 v[220:223], v158 offset:39936
	s_waitcnt vmcnt(8) lgkmcnt(0)
	s_setprio 3
	s_barrier
	v_mfma_f32_16x16x32_bf16 v[124:127], v[148:151], v[188:191], v[124:127]
	v_mfma_f32_16x16x32_bf16 v[120:123], v[164:167], v[188:191], v[120:123]
	v_mfma_f32_16x16x32_bf16 v[108:111], v[148:151], v[196:199], v[108:111]
	v_mfma_f32_16x16x32_bf16 v[104:107], v[164:167], v[196:199], v[104:107]
	v_mfma_f32_16x16x32_bf16 v[92:95], v[148:151], v[208:211], v[92:95]
	v_mfma_f32_16x16x32_bf16 v[88:91], v[164:167], v[208:211], v[88:91]
	v_mfma_f32_16x16x32_bf16 v[76:79], v[148:151], v[216:219], v[76:79]
	v_mfma_f32_16x16x32_bf16 v[72:75], v[164:167], v[216:219], v[72:75]
	v_mfma_f32_16x16x32_bf16 v[124:127], v[160:163], v[192:195], v[124:127]
	v_mfma_f32_16x16x32_bf16 v[120:123], v[168:171], v[192:195], v[120:123]
	v_mfma_f32_16x16x32_bf16 v[108:111], v[160:163], v[200:203], v[108:111]
	v_mfma_f32_16x16x32_bf16 v[104:107], v[168:171], v[200:203], v[104:107]
	v_mfma_f32_16x16x32_bf16 v[92:95], v[160:163], v[212:215], v[92:95]
	v_mfma_f32_16x16x32_bf16 v[88:91], v[168:171], v[212:215], v[88:91]
	v_mfma_f32_16x16x32_bf16 v[76:79], v[160:163], v[220:223], v[76:79]
	v_mfma_f32_16x16x32_bf16 v[72:75], v[168:171], v[220:223], v[72:75]
	v_mfma_f32_16x16x32_bf16 v[116:119], v[172:175], v[188:191], v[116:119]
	v_mfma_f32_16x16x32_bf16 v[112:115], v[180:183], v[188:191], v[112:115]
	v_mfma_f32_16x16x32_bf16 v[100:103], v[172:175], v[196:199], v[100:103]
	v_mfma_f32_16x16x32_bf16 v[96:99], v[180:183], v[196:199], v[96:99]
	v_mfma_f32_16x16x32_bf16 v[84:87], v[172:175], v[208:211], v[84:87]
	v_mfma_f32_16x16x32_bf16 v[80:83], v[180:183], v[208:211], v[80:83]
	v_mfma_f32_16x16x32_bf16 v[68:71], v[172:175], v[216:219], v[68:71]
	v_mfma_f32_16x16x32_bf16 v[64:67], v[180:183], v[216:219], v[64:67]
	v_mfma_f32_16x16x32_bf16 v[116:119], v[176:179], v[192:195], v[116:119]
	v_mfma_f32_16x16x32_bf16 v[112:115], v[184:187], v[192:195], v[112:115]
	v_mfma_f32_16x16x32_bf16 v[100:103], v[176:179], v[200:203], v[100:103]
	v_mfma_f32_16x16x32_bf16 v[96:99], v[184:187], v[200:203], v[96:99]
	v_mfma_f32_16x16x32_bf16 v[84:87], v[176:179], v[212:215], v[84:87]
	v_mfma_f32_16x16x32_bf16 v[80:83], v[184:187], v[212:215], v[80:83]
	v_mfma_f32_16x16x32_bf16 v[68:71], v[176:179], v[220:223], v[68:71]
	v_mfma_f32_16x16x32_bf16 v[64:67], v[184:187], v[220:223], v[64:67]
	s_barrier
	s_setprio 0
	s_add_i32 s0, s0, s41
	s_add_u32 s100, s36, 0x80
	s_addc_u32 s101, s37, 0
	s_mov_b32 m0, s0
	ds_read_b128 v[188:191], v158 offset:49152
	global_load_lds_dwordx4 v132, s[100:101]
	s_add_i32 m0, s0, 0x2000
	ds_read_b128 v[192:195], v158 offset:50176
	global_load_lds_dwordx4 v136, s[100:101]
	s_add_u32 s36, s36, 0x100080
	s_addc_u32 s37, s37, 0
	s_add_i32 s0, s1, s41
	s_mov_b32 m0, s0
	ds_read_b128 v[196:199], v158 offset:51200
	global_load_lds_dwordx4 v132, s[36:37]
	s_add_i32 m0, s0, 0x2000
	ds_read_b128 v[200:203], v158 offset:52224
	global_load_lds_dwordx4 v136, s[36:37]
	s_add_u32 s100, s38, 0xfff00080
	s_addc_u32 s101, s39, -1
	s_mov_b32 m0, s46
	ds_read_b128 v[208:211], v158 offset:53248
	global_load_lds_dwordx4 v130, s[100:101]
	s_mov_b32 m0, s47
	ds_read_b128 v[212:215], v158 offset:54272
	global_load_lds_dwordx4 v134, s[100:101]
	ds_read_b128 v[216:219], v158 offset:55296
	ds_read_b128 v[220:223], v158 offset:56320
	s_waitcnt vmcnt(8) lgkmcnt(0)
	s_setprio 3
	s_barrier
	v_mfma_f32_16x16x32_bf16 v[60:63], v[148:151], v[188:191], v[60:63]
	v_mfma_f32_16x16x32_bf16 v[56:59], v[164:167], v[188:191], v[56:59]
	v_mfma_f32_16x16x32_bf16 v[44:47], v[148:151], v[196:199], v[44:47]
	v_mfma_f32_16x16x32_bf16 v[40:43], v[164:167], v[196:199], v[40:43]
	v_mfma_f32_16x16x32_bf16 v[28:31], v[148:151], v[208:211], v[28:31]
	v_mfma_f32_16x16x32_bf16 v[24:27], v[164:167], v[208:211], v[24:27]
	v_mfma_f32_16x16x32_bf16 v[12:15], v[148:151], v[216:219], v[12:15]
	v_mfma_f32_16x16x32_bf16 v[8:11], v[164:167], v[216:219], v[8:11]
	v_mfma_f32_16x16x32_bf16 v[60:63], v[160:163], v[192:195], v[60:63]
	v_mfma_f32_16x16x32_bf16 v[56:59], v[168:171], v[192:195], v[56:59]
	v_mfma_f32_16x16x32_bf16 v[44:47], v[160:163], v[200:203], v[44:47]
	v_mfma_f32_16x16x32_bf16 v[40:43], v[168:171], v[200:203], v[40:43]
	v_mfma_f32_16x16x32_bf16 v[28:31], v[160:163], v[212:215], v[28:31]
	v_mfma_f32_16x16x32_bf16 v[24:27], v[168:171], v[212:215], v[24:27]
	v_mfma_f32_16x16x32_bf16 v[12:15], v[160:163], v[220:223], v[12:15]
	v_mfma_f32_16x16x32_bf16 v[8:11], v[168:171], v[220:223], v[8:11]
	v_mfma_f32_16x16x32_bf16 v[52:55], v[172:175], v[188:191], v[52:55]
	v_mfma_f32_16x16x32_bf16 v[48:51], v[180:183], v[188:191], v[48:51]
	v_mfma_f32_16x16x32_bf16 v[36:39], v[172:175], v[196:199], v[36:39]
	v_mfma_f32_16x16x32_bf16 v[32:35], v[180:183], v[196:199], v[32:35]
	v_mfma_f32_16x16x32_bf16 v[20:23], v[172:175], v[208:211], v[20:23]
	v_mfma_f32_16x16x32_bf16 v[16:19], v[180:183], v[208:211], v[16:19]
	v_mfma_f32_16x16x32_bf16 v[4:7], v[172:175], v[216:219], v[4:7]
	v_mfma_f32_16x16x32_bf16 v[0:3], v[180:183], v[216:219], v[0:3]
	v_mfma_f32_16x16x32_bf16 v[52:55], v[176:179], v[192:195], v[52:55]
	v_mfma_f32_16x16x32_bf16 v[48:51], v[184:187], v[192:195], v[48:51]
	v_mfma_f32_16x16x32_bf16 v[36:39], v[176:179], v[200:203], v[36:39]
	v_mfma_f32_16x16x32_bf16 v[32:35], v[184:187], v[200:203], v[32:35]
	v_mfma_f32_16x16x32_bf16 v[20:23], v[176:179], v[212:215], v[20:23]
	v_mfma_f32_16x16x32_bf16 v[16:19], v[184:187], v[212:215], v[16:19]
	v_mfma_f32_16x16x32_bf16 v[4:7], v[176:179], v[220:223], v[4:7]
	v_mfma_f32_16x16x32_bf16 v[0:3], v[184:187], v[220:223], v[0:3]
	s_barrier
	s_setprio 0
	s_add_u32 s34, s34, 0x100
	s_addc_u32 s35, s35, 0
	s_add_i32 s60, s60, 2
	s_add_u32 s58, s58, 0x100
	s_addc_u32 s59, s59, 0
	s_cmp_gt_u32 s60, 61
	s_cbranch_scc0 .LBB0_134
	s_and_b64 vcc, exec, s[10:11]
	s_cbranch_vccz .LBB0_137
	s_barrier

.LBB0_425:
	ds_read_b128 v[146:149], v214
	ds_read_b128 v[150:153], v214 offset:1024
	ds_read_b128 v[154:157], v214 offset:2048
	ds_read_b128 v[158:161], v214 offset:3072
	ds_read_b128 v[162:165], v215
	ds_read_b128 v[166:169], v215 offset:1024
	ds_read_b128 v[170:173], v215 offset:2048
	ds_read_b128 v[174:177], v215 offset:3072
	s_add_i32 s13, s13, 2
	s_lshr_b32 s0, s13, 6
	s_mul_hi_u32 s1, s0, 0x8200000
	s_mul_i32 s0, s0, 0x8200000
	s_add_u32 s0, s46, s0
	s_addc_u32 s1, s47, s1
	s_and_b32 s35, s35, 0x1f00
	s_add_u32 s0, s0, s35
	s_addc_u32 s1, s1, 0
	s_add_u32 s0, s0, 0x100080
	s_addc_u32 s1, s1, 0
	s_add_i32 m0, s43, 0xc000
	ds_read_b128 v[178:181], v145
	ds_read_b128 v[182:185], v145 offset:1024
	ds_read_b128 v[186:189], v145 offset:2048
	ds_read_b128 v[190:193], v145 offset:3072
	ds_read_b128 v[194:197], v145 offset:4096
	ds_read_b128 v[198:201], v145 offset:5120
	ds_read_b128 v[202:205], v145 offset:6144
	global_load_lds_dwordx4 v128, s[0:1]
	s_add_i32 m0, s43, 0xe000
	ds_read_b128 v[206:209], v145 offset:7168
	global_load_lds_dwordx4 v132, s[0:1]
	s_waitcnt vmcnt(8) lgkmcnt(0)
	s_setprio 3
	s_barrier
	v_mfma_f32_16x16x32_bf16 v[124:127], v[146:149], v[178:181], v[124:127]
	v_mfma_f32_16x16x32_bf16 v[120:123], v[154:157], v[178:181], v[120:123]
	v_mfma_f32_16x16x32_bf16 v[116:119], v[146:149], v[186:189], v[116:119]
	v_mfma_f32_16x16x32_bf16 v[108:111], v[154:157], v[186:189], v[108:111]
	v_mfma_f32_16x16x32_bf16 v[100:103], v[146:149], v[194:197], v[100:103]
	v_mfma_f32_16x16x32_bf16 v[92:95], v[154:157], v[194:197], v[92:95]
	v_mfma_f32_16x16x32_bf16 v[84:87], v[146:149], v[202:205], v[84:87]
	v_mfma_f32_16x16x32_bf16 v[76:79], v[154:157], v[202:205], v[76:79]
	v_mfma_f32_16x16x32_bf16 v[124:127], v[150:153], v[182:185], v[124:127]
	v_mfma_f32_16x16x32_bf16 v[120:123], v[158:161], v[182:185], v[120:123]
	v_mfma_f32_16x16x32_bf16 v[116:119], v[150:153], v[190:193], v[116:119]
	v_mfma_f32_16x16x32_bf16 v[108:111], v[158:161], v[190:193], v[108:111]
	v_mfma_f32_16x16x32_bf16 v[100:103], v[150:153], v[198:201], v[100:103]
	v_mfma_f32_16x16x32_bf16 v[92:95], v[158:161], v[198:201], v[92:95]
	v_mfma_f32_16x16x32_bf16 v[84:87], v[150:153], v[206:209], v[84:87]
	v_mfma_f32_16x16x32_bf16 v[76:79], v[158:161], v[206:209], v[76:79]
	v_mfma_f32_16x16x32_bf16 v[112:115], v[162:165], v[178:181], v[112:115]
	v_mfma_f32_16x16x32_bf16 v[104:107], v[170:173], v[178:181], v[104:107]
	v_mfma_f32_16x16x32_bf16 v[96:99], v[162:165], v[186:189], v[96:99]
	v_mfma_f32_16x16x32_bf16 v[88:91], v[170:173], v[186:189], v[88:91]
	v_mfma_f32_16x16x32_bf16 v[80:83], v[162:165], v[194:197], v[80:83]
	v_mfma_f32_16x16x32_bf16 v[72:75], v[170:173], v[194:197], v[72:75]
	v_mfma_f32_16x16x32_bf16 v[68:71], v[162:165], v[202:205], v[68:71]
	v_mfma_f32_16x16x32_bf16 v[64:67], v[170:173], v[202:205], v[64:67]
	v_mfma_f32_16x16x32_bf16 v[112:115], v[166:169], v[182:185], v[112:115]
	v_mfma_f32_16x16x32_bf16 v[104:107], v[174:177], v[182:185], v[104:107]
	v_mfma_f32_16x16x32_bf16 v[96:99], v[166:169], v[190:193], v[96:99]
	v_mfma_f32_16x16x32_bf16 v[88:91], v[174:177], v[190:193], v[88:91]
	v_mfma_f32_16x16x32_bf16 v[80:83], v[166:169], v[198:201], v[80:83]
	v_mfma_f32_16x16x32_bf16 v[72:75], v[174:177], v[198:201], v[72:75]
	v_mfma_f32_16x16x32_bf16 v[68:71], v[166:169], v[206:209], v[68:71]
	v_mfma_f32_16x16x32_bf16 v[64:67], v[174:177], v[206:209], v[64:67]
	s_barrier
	s_setprio 0
	s_add_i32 s0, s67, s59
	s_mov_b32 m0, s0
	ds_read_b128 v[178:181], v145 offset:16384
	ds_read_b128 v[182:185], v145 offset:17408
	ds_read_b128 v[186:189], v145 offset:18432
	ds_read_b128 v[190:193], v145 offset:19456
	ds_read_b128 v[194:197], v145 offset:20480
	global_load_lds_dwordx4 v130, s[52:53]
	s_add_i32 m0, s0, 0x2000
	s_add_u32 s0, s52, 0x100000
	s_addc_u32 s1, s53, 0
	s_add_i32 s35, s68, s59
	global_load_lds_dwordx4 v134, s[52:53]
	s_mov_b32 m0, s35
	s_nop 0
	global_load_lds_dwordx4 v130, s[0:1]
	s_add_i32 m0, s35, 0x2000
	ds_read_b128 v[206:209], v145 offset:23552
	global_load_lds_dwordx4 v134, s[0:1]
	s_mov_b32 m0, s43
	ds_read_b128 v[202:205], v145 offset:22528
	global_load_lds_dwordx4 v128, s[54:55]
	s_mov_b32 m0, s62
	ds_read_b128 v[198:201], v145 offset:21504
	global_load_lds_dwordx4 v132, s[54:55]
	s_waitcnt vmcnt(8) lgkmcnt(0)
	s_setprio 3
	s_barrier
	v_mfma_f32_16x16x32_bf16 v[60:63], v[146:149], v[178:181], v[60:63]
	v_mfma_f32_16x16x32_bf16 v[56:59], v[154:157], v[178:181], v[56:59]
	v_mfma_f32_16x16x32_bf16 v[52:55], v[146:149], v[186:189], v[52:55]
	v_mfma_f32_16x16x32_bf16 v[44:47], v[154:157], v[186:189], v[44:47]
	v_mfma_f32_16x16x32_bf16 v[36:39], v[146:149], v[194:197], v[36:39]
	v_mfma_f32_16x16x32_bf16 v[28:31], v[154:157], v[194:197], v[28:31]
	v_mfma_f32_16x16x32_bf16 v[20:23], v[146:149], v[202:205], v[20:23]
	v_mfma_f32_16x16x32_bf16 v[12:15], v[154:157], v[202:205], v[12:15]
	v_mfma_f32_16x16x32_bf16 v[60:63], v[150:153], v[182:185], v[60:63]
	v_mfma_f32_16x16x32_bf16 v[56:59], v[158:161], v[182:185], v[56:59]
	v_mfma_f32_16x16x32_bf16 v[52:55], v[150:153], v[190:193], v[52:55]
	v_mfma_f32_16x16x32_bf16 v[44:47], v[158:161], v[190:193], v[44:47]
	v_mfma_f32_16x16x32_bf16 v[36:39], v[150:153], v[198:201], v[36:39]
	v_mfma_f32_16x16x32_bf16 v[28:31], v[158:161], v[198:201], v[28:31]
	v_mfma_f32_16x16x32_bf16 v[20:23], v[150:153], v[206:209], v[20:23]
	v_mfma_f32_16x16x32_bf16 v[12:15], v[158:161], v[206:209], v[12:15]
	v_mfma_f32_16x16x32_bf16 v[48:51], v[162:165], v[178:181], v[48:51]
	v_mfma_f32_16x16x32_bf16 v[40:43], v[170:173], v[178:181], v[40:43]
	v_mfma_f32_16x16x32_bf16 v[32:35], v[162:165], v[186:189], v[32:35]
	v_mfma_f32_16x16x32_bf16 v[24:27], v[170:173], v[186:189], v[24:27]
	v_mfma_f32_16x16x32_bf16 v[16:19], v[162:165], v[194:197], v[16:19]
	v_mfma_f32_16x16x32_bf16 v[8:11], v[170:173], v[194:197], v[8:11]
	v_mfma_f32_16x16x32_bf16 v[4:7], v[162:165], v[202:205], v[4:7]
	v_mfma_f32_16x16x32_bf16 v[0:3], v[170:173], v[202:205], v[0:3]
	v_mfma_f32_16x16x32_bf16 v[48:51], v[166:169], v[182:185], v[48:51]
	v_mfma_f32_16x16x32_bf16 v[40:43], v[174:177], v[182:185], v[40:43]
	v_mfma_f32_16x16x32_bf16 v[32:35], v[166:169], v[190:193], v[32:35]
	v_mfma_f32_16x16x32_bf16 v[24:27], v[174:177], v[190:193], v[24:27]
	v_mfma_f32_16x16x32_bf16 v[16:19], v[166:169], v[198:201], v[16:19]
	v_mfma_f32_16x16x32_bf16 v[8:11], v[174:177], v[198:201], v[8:11]
	v_mfma_f32_16x16x32_bf16 v[4:7], v[166:169], v[206:209], v[4:7]
	v_mfma_f32_16x16x32_bf16 v[0:3], v[174:177], v[206:209], v[0:3]
	s_barrier
	s_setprio 0
	s_add_i32 s35, 0, 0x18000
	s_add_i32 s37, 0, 0x1c000
	ds_read_b128 v[146:149], v216
	ds_read_b128 v[150:153], v216 offset:1024
	ds_read_b128 v[154:157], v216 offset:2048
	ds_read_b128 v[158:161], v216 offset:3072
	ds_read_b128 v[162:165], v217
	ds_read_b128 v[166:169], v217 offset:1024
	ds_read_b128 v[170:173], v217 offset:2048
	ds_read_b128 v[174:177], v217 offset:3072
	s_add_u32 s0, s54, 0x100000
	s_addc_u32 s1, s55, 0
	s_mov_b32 m0, s63
	ds_read_b128 v[178:181], v145 offset:32768
	ds_read_b128 v[182:185], v145 offset:33792
	ds_read_b128 v[186:189], v145 offset:34816
	ds_read_b128 v[190:193], v145 offset:35840
	ds_read_b128 v[194:197], v145 offset:36864
	ds_read_b128 v[198:201], v145 offset:37888
	ds_read_b128 v[202:205], v145 offset:38912
	global_load_lds_dwordx4 v128, s[0:1]
	s_mov_b32 m0, s64
	ds_read_b128 v[206:209], v145 offset:39936
	global_load_lds_dwordx4 v132, s[0:1]
	s_waitcnt vmcnt(8) lgkmcnt(0)
	s_setprio 3
	s_barrier
	v_mfma_f32_16x16x32_bf16 v[124:127], v[146:149], v[178:181], v[124:127]
	v_mfma_f32_16x16x32_bf16 v[120:123], v[154:157], v[178:181], v[120:123]
	v_mfma_f32_16x16x32_bf16 v[116:119], v[146:149], v[186:189], v[116:119]
	v_mfma_f32_16x16x32_bf16 v[108:111], v[154:157], v[186:189], v[108:111]
	v_mfma_f32_16x16x32_bf16 v[100:103], v[146:149], v[194:197], v[100:103]
	v_mfma_f32_16x16x32_bf16 v[92:95], v[154:157], v[194:197], v[92:95]
	v_mfma_f32_16x16x32_bf16 v[84:87], v[146:149], v[202:205], v[84:87]
	v_mfma_f32_16x16x32_bf16 v[76:79], v[154:157], v[202:205], v[76:79]
	v_mfma_f32_16x16x32_bf16 v[124:127], v[150:153], v[182:185], v[124:127]
	v_mfma_f32_16x16x32_bf16 v[120:123], v[158:161], v[182:185], v[120:123]
	v_mfma_f32_16x16x32_bf16 v[116:119], v[150:153], v[190:193], v[116:119]
	v_mfma_f32_16x16x32_bf16 v[108:111], v[158:161], v[190:193], v[108:111]
	v_mfma_f32_16x16x32_bf16 v[100:103], v[150:153], v[198:201], v[100:103]
	v_mfma_f32_16x16x32_bf16 v[92:95], v[158:161], v[198:201], v[92:95]
	v_mfma_f32_16x16x32_bf16 v[84:87], v[150:153], v[206:209], v[84:87]
	v_mfma_f32_16x16x32_bf16 v[76:79], v[158:161], v[206:209], v[76:79]
	v_mfma_f32_16x16x32_bf16 v[112:115], v[162:165], v[178:181], v[112:115]
	v_mfma_f32_16x16x32_bf16 v[104:107], v[170:173], v[178:181], v[104:107]
	v_mfma_f32_16x16x32_bf16 v[96:99], v[162:165], v[186:189], v[96:99]
	v_mfma_f32_16x16x32_bf16 v[88:91], v[170:173], v[186:189], v[88:91]
	v_mfma_f32_16x16x32_bf16 v[80:83], v[162:165], v[194:197], v[80:83]
	v_mfma_f32_16x16x32_bf16 v[72:75], v[170:173], v[194:197], v[72:75]
	v_mfma_f32_16x16x32_bf16 v[68:71], v[162:165], v[202:205], v[68:71]
	v_mfma_f32_16x16x32_bf16 v[64:67], v[170:173], v[202:205], v[64:67]
	v_mfma_f32_16x16x32_bf16 v[112:115], v[166:169], v[182:185], v[112:115]
	v_mfma_f32_16x16x32_bf16 v[104:107], v[174:177], v[182:185], v[104:107]
	v_mfma_f32_16x16x32_bf16 v[96:99], v[166:169], v[190:193], v[96:99]
	v_mfma_f32_16x16x32_bf16 v[88:91], v[174:177], v[190:193], v[88:91]
	v_mfma_f32_16x16x32_bf16 v[80:83], v[166:169], v[198:201], v[80:83]
	v_mfma_f32_16x16x32_bf16 v[72:75], v[174:177], v[198:201], v[72:75]
	v_mfma_f32_16x16x32_bf16 v[68:71], v[166:169], v[206:209], v[68:71]
	v_mfma_f32_16x16x32_bf16 v[64:67], v[174:177], v[206:209], v[64:67]
	s_barrier
	s_setprio 0
	s_add_i32 s0, s35, s59
	s_add_u32 s100, s52, 0x80
	s_addc_u32 s101, s53, 0
	s_mov_b32 m0, s0
	ds_read_b128 v[178:181], v145 offset:49152
	ds_read_b128 v[182:185], v145 offset:50176
	ds_read_b128 v[186:189], v145 offset:51200
	ds_read_b128 v[190:193], v145 offset:52224
	global_load_lds_dwordx4 v130, s[100:101]
	s_add_i32 m0, s0, 0x2000
	s_add_u32 s0, s52, 0x100080
	s_addc_u32 s1, s53, 0
	s_add_i32 s35, s37, s59
	global_load_lds_dwordx4 v134, s[100:101]
	s_mov_b32 m0, s35
	ds_read_b128 v[206:209], v145 offset:56320
	global_load_lds_dwordx4 v130, s[0:1]
	s_add_i32 m0, s35, 0x2000
	ds_read_b128 v[202:205], v145 offset:55296
	global_load_lds_dwordx4 v134, s[0:1]
	s_add_u32 s100, s54, 0x80
	s_addc_u32 s101, s55, 0
	s_mov_b32 m0, s60
	ds_read_b128 v[198:201], v145 offset:54272
	global_load_lds_dwordx4 v128, s[100:101]
	s_mov_b32 m0, s65
	ds_read_b128 v[194:197], v145 offset:53248
	global_load_lds_dwordx4 v132, s[100:101]
	s_waitcnt vmcnt(8) lgkmcnt(0)
	s_setprio 3
	s_barrier
	v_mfma_f32_16x16x32_bf16 v[60:63], v[146:149], v[178:181], v[60:63]
	v_mfma_f32_16x16x32_bf16 v[56:59], v[154:157], v[178:181], v[56:59]
	v_mfma_f32_16x16x32_bf16 v[52:55], v[146:149], v[186:189], v[52:55]
	v_mfma_f32_16x16x32_bf16 v[44:47], v[154:157], v[186:189], v[44:47]
	v_mfma_f32_16x16x32_bf16 v[36:39], v[146:149], v[194:197], v[36:39]
	v_mfma_f32_16x16x32_bf16 v[28:31], v[154:157], v[194:197], v[28:31]
	v_mfma_f32_16x16x32_bf16 v[20:23], v[146:149], v[202:205], v[20:23]
	v_mfma_f32_16x16x32_bf16 v[12:15], v[154:157], v[202:205], v[12:15]
	v_mfma_f32_16x16x32_bf16 v[60:63], v[150:153], v[182:185], v[60:63]
	v_mfma_f32_16x16x32_bf16 v[56:59], v[158:161], v[182:185], v[56:59]
	v_mfma_f32_16x16x32_bf16 v[52:55], v[150:153], v[190:193], v[52:55]
	v_mfma_f32_16x16x32_bf16 v[44:47], v[158:161], v[190:193], v[44:47]
	v_mfma_f32_16x16x32_bf16 v[36:39], v[150:153], v[198:201], v[36:39]
	v_mfma_f32_16x16x32_bf16 v[28:31], v[158:161], v[198:201], v[28:31]
	v_mfma_f32_16x16x32_bf16 v[20:23], v[150:153], v[206:209], v[20:23]
	v_mfma_f32_16x16x32_bf16 v[12:15], v[158:161], v[206:209], v[12:15]
	v_mfma_f32_16x16x32_bf16 v[48:51], v[162:165], v[178:181], v[48:51]
	v_mfma_f32_16x16x32_bf16 v[40:43], v[170:173], v[178:181], v[40:43]
	v_mfma_f32_16x16x32_bf16 v[32:35], v[162:165], v[186:189], v[32:35]
	v_mfma_f32_16x16x32_bf16 v[24:27], v[170:173], v[186:189], v[24:27]
	v_mfma_f32_16x16x32_bf16 v[16:19], v[162:165], v[194:197], v[16:19]
	v_mfma_f32_16x16x32_bf16 v[8:11], v[170:173], v[194:197], v[8:11]
	v_mfma_f32_16x16x32_bf16 v[4:7], v[162:165], v[202:205], v[4:7]
	v_mfma_f32_16x16x32_bf16 v[0:3], v[170:173], v[202:205], v[0:3]
	v_mfma_f32_16x16x32_bf16 v[48:51], v[166:169], v[182:185], v[48:51]
	v_mfma_f32_16x16x32_bf16 v[40:43], v[174:177], v[182:185], v[40:43]
	v_mfma_f32_16x16x32_bf16 v[32:35], v[166:169], v[190:193], v[32:35]
	v_mfma_f32_16x16x32_bf16 v[24:27], v[174:177], v[190:193], v[24:27]
	v_mfma_f32_16x16x32_bf16 v[16:19], v[166:169], v[198:201], v[16:19]
	v_mfma_f32_16x16x32_bf16 v[8:11], v[174:177], v[198:201], v[8:11]
	v_mfma_f32_16x16x32_bf16 v[4:7], v[166:169], v[206:209], v[4:7]
	v_mfma_f32_16x16x32_bf16 v[0:3], v[174:177], v[206:209], v[0:3]
	s_barrier
	s_setprio 0
	s_cmpk_gt_u32 s13, 0xa9
	s_mov_b32 s35, s4
	s_cbranch_scc1 .LBB0_432

.LBB0_677:
	ds_read_b128 v[156:159], v152
	ds_read_b128 v[160:163], v152 offset:1024
	ds_read_b128 v[164:167], v152 offset:2048
	ds_read_b128 v[168:171], v152 offset:3072
	ds_read_b128 v[172:175], v153
	ds_read_b128 v[176:179], v153 offset:1024
	ds_read_b128 v[180:183], v153 offset:2048
	ds_read_b128 v[184:187], v153 offset:3072
	s_add_u32 s0, s36, 0xfff00080
	s_addc_u32 s1, s37, -1
	s_cmp_eq_u32 s61, 60
	s_cselect_b32 s41, s56, s1
	s_cselect_b32 s40, s57, s0
	s_cselect_b32 s39, s15, s60
	s_cselect_b32 s38, s58, s59
	s_add_i32 m0, s31, 0xc000
	ds_read_b128 v[188:191], v154
	ds_read_b128 v[192:195], v154 offset:1024
	ds_read_b128 v[196:199], v154 offset:2048
	ds_read_b128 v[200:203], v154 offset:3072
	ds_read_b128 v[204:207], v154 offset:4096
	ds_read_b128 v[208:211], v154 offset:5120
	ds_read_b128 v[212:215], v154 offset:6144
	global_load_lds_dwordx4 v138, s[36:37]
	s_add_i32 m0, s31, 0xe000
	ds_read_b128 v[216:219], v154 offset:7168
	global_load_lds_dwordx4 v140, s[36:37]
	s_waitcnt vmcnt(8) lgkmcnt(0)
	s_setprio 3
	s_barrier
	v_mfma_f32_16x16x32_bf16 v[124:127], v[156:159], v[188:191], v[124:127]
	v_mfma_f32_16x16x32_bf16 v[120:123], v[164:167], v[188:191], v[120:123]
	v_mfma_f32_16x16x32_bf16 v[108:111], v[156:159], v[196:199], v[108:111]
	v_mfma_f32_16x16x32_bf16 v[104:107], v[164:167], v[196:199], v[104:107]
	v_mfma_f32_16x16x32_bf16 v[92:95], v[156:159], v[204:207], v[92:95]
	v_mfma_f32_16x16x32_bf16 v[88:91], v[164:167], v[204:207], v[88:91]
	v_mfma_f32_16x16x32_bf16 v[76:79], v[156:159], v[212:215], v[76:79]
	v_mfma_f32_16x16x32_bf16 v[72:75], v[164:167], v[212:215], v[72:75]
	v_mfma_f32_16x16x32_bf16 v[124:127], v[160:163], v[192:195], v[124:127]
	v_mfma_f32_16x16x32_bf16 v[120:123], v[168:171], v[192:195], v[120:123]
	v_mfma_f32_16x16x32_bf16 v[108:111], v[160:163], v[200:203], v[108:111]
	v_mfma_f32_16x16x32_bf16 v[104:107], v[168:171], v[200:203], v[104:107]
	v_mfma_f32_16x16x32_bf16 v[92:95], v[160:163], v[208:211], v[92:95]
	v_mfma_f32_16x16x32_bf16 v[88:91], v[168:171], v[208:211], v[88:91]
	v_mfma_f32_16x16x32_bf16 v[76:79], v[160:163], v[216:219], v[76:79]
	v_mfma_f32_16x16x32_bf16 v[72:75], v[168:171], v[216:219], v[72:75]
	v_mfma_f32_16x16x32_bf16 v[116:119], v[172:175], v[188:191], v[116:119]
	v_mfma_f32_16x16x32_bf16 v[112:115], v[180:183], v[188:191], v[112:115]
	v_mfma_f32_16x16x32_bf16 v[100:103], v[172:175], v[196:199], v[100:103]
	v_mfma_f32_16x16x32_bf16 v[96:99], v[180:183], v[196:199], v[96:99]
	v_mfma_f32_16x16x32_bf16 v[84:87], v[172:175], v[204:207], v[84:87]
	v_mfma_f32_16x16x32_bf16 v[80:83], v[180:183], v[204:207], v[80:83]
	v_mfma_f32_16x16x32_bf16 v[68:71], v[172:175], v[212:215], v[68:71]
	v_mfma_f32_16x16x32_bf16 v[64:67], v[180:183], v[212:215], v[64:67]
	v_mfma_f32_16x16x32_bf16 v[116:119], v[176:179], v[192:195], v[116:119]
	v_mfma_f32_16x16x32_bf16 v[112:115], v[184:187], v[192:195], v[112:115]
	v_mfma_f32_16x16x32_bf16 v[100:103], v[176:179], v[200:203], v[100:103]
	v_mfma_f32_16x16x32_bf16 v[96:99], v[184:187], v[200:203], v[96:99]
	v_mfma_f32_16x16x32_bf16 v[84:87], v[176:179], v[208:211], v[84:87]
	v_mfma_f32_16x16x32_bf16 v[80:83], v[184:187], v[208:211], v[80:83]
	v_mfma_f32_16x16x32_bf16 v[68:71], v[176:179], v[216:219], v[68:71]
	v_mfma_f32_16x16x32_bf16 v[64:67], v[184:187], v[216:219], v[64:67]
	s_barrier
	s_setprio 0
	s_add_i32 s0, s51, s43
	s_mov_b32 m0, s0
	ds_read_b128 v[188:191], v154 offset:16384
	ds_read_b128 v[192:195], v154 offset:17408
	ds_read_b128 v[196:199], v154 offset:18432
	ds_read_b128 v[200:203], v154 offset:19456
	ds_read_b128 v[204:207], v154 offset:20480
	global_load_lds_dwordx4 v130, s[38:39]
	s_add_i32 m0, s0, 0x2000
	s_add_u32 s0, s38, 0x100000
	s_addc_u32 s1, s39, 0
	s_add_i32 s62, s52, s43
	global_load_lds_dwordx4 v134, s[38:39]
	s_mov_b32 m0, s62
	s_nop 0
	global_load_lds_dwordx4 v130, s[0:1]
	s_add_i32 m0, s62, 0x2000
	ds_read_b128 v[216:219], v154 offset:23552
	global_load_lds_dwordx4 v134, s[0:1]
	s_mov_b32 m0, s31
	ds_read_b128 v[212:215], v154 offset:22528
	global_load_lds_dwordx4 v128, s[40:41]
	s_mov_b32 m0, s35
	ds_read_b128 v[208:211], v154 offset:21504
	global_load_lds_dwordx4 v132, s[40:41]
	s_waitcnt vmcnt(8) lgkmcnt(0)
	s_setprio 3
	s_barrier
	v_mfma_f32_16x16x32_bf16 v[60:63], v[156:159], v[188:191], v[60:63]
	v_mfma_f32_16x16x32_bf16 v[56:59], v[164:167], v[188:191], v[56:59]
	v_mfma_f32_16x16x32_bf16 v[44:47], v[156:159], v[196:199], v[44:47]
	v_mfma_f32_16x16x32_bf16 v[40:43], v[164:167], v[196:199], v[40:43]
	v_mfma_f32_16x16x32_bf16 v[28:31], v[156:159], v[204:207], v[28:31]
	v_mfma_f32_16x16x32_bf16 v[24:27], v[164:167], v[204:207], v[24:27]
	v_mfma_f32_16x16x32_bf16 v[12:15], v[156:159], v[212:215], v[12:15]
	v_mfma_f32_16x16x32_bf16 v[8:11], v[164:167], v[212:215], v[8:11]
	v_mfma_f32_16x16x32_bf16 v[60:63], v[160:163], v[192:195], v[60:63]
	v_mfma_f32_16x16x32_bf16 v[56:59], v[168:171], v[192:195], v[56:59]
	v_mfma_f32_16x16x32_bf16 v[44:47], v[160:163], v[200:203], v[44:47]
	v_mfma_f32_16x16x32_bf16 v[40:43], v[168:171], v[200:203], v[40:43]
	v_mfma_f32_16x16x32_bf16 v[28:31], v[160:163], v[208:211], v[28:31]
	v_mfma_f32_16x16x32_bf16 v[24:27], v[168:171], v[208:211], v[24:27]
	v_mfma_f32_16x16x32_bf16 v[12:15], v[160:163], v[216:219], v[12:15]
	v_mfma_f32_16x16x32_bf16 v[8:11], v[168:171], v[216:219], v[8:11]
	v_mfma_f32_16x16x32_bf16 v[52:55], v[172:175], v[188:191], v[52:55]
	v_mfma_f32_16x16x32_bf16 v[48:51], v[180:183], v[188:191], v[48:51]
	v_mfma_f32_16x16x32_bf16 v[36:39], v[172:175], v[196:199], v[36:39]
	v_mfma_f32_16x16x32_bf16 v[32:35], v[180:183], v[196:199], v[32:35]
	v_mfma_f32_16x16x32_bf16 v[20:23], v[172:175], v[204:207], v[20:23]
	v_mfma_f32_16x16x32_bf16 v[16:19], v[180:183], v[204:207], v[16:19]
	v_mfma_f32_16x16x32_bf16 v[4:7], v[172:175], v[212:215], v[4:7]
	v_mfma_f32_16x16x32_bf16 v[0:3], v[180:183], v[212:215], v[0:3]
	v_mfma_f32_16x16x32_bf16 v[52:55], v[176:179], v[192:195], v[52:55]
	v_mfma_f32_16x16x32_bf16 v[48:51], v[184:187], v[192:195], v[48:51]
	v_mfma_f32_16x16x32_bf16 v[36:39], v[176:179], v[200:203], v[36:39]
	v_mfma_f32_16x16x32_bf16 v[32:35], v[184:187], v[200:203], v[32:35]
	v_mfma_f32_16x16x32_bf16 v[20:23], v[176:179], v[208:211], v[20:23]
	v_mfma_f32_16x16x32_bf16 v[16:19], v[184:187], v[208:211], v[16:19]
	v_mfma_f32_16x16x32_bf16 v[4:7], v[176:179], v[216:219], v[4:7]
	v_mfma_f32_16x16x32_bf16 v[0:3], v[184:187], v[216:219], v[0:3]
	s_barrier
	s_setprio 0
	s_add_i32 s62, 0, 0x18000
	s_add_i32 s63, 0, 0x1c000
	ds_read_b128 v[156:159], v226
	ds_read_b128 v[160:163], v226 offset:1024
	ds_read_b128 v[164:167], v226 offset:2048
	ds_read_b128 v[168:171], v226 offset:3072
	ds_read_b128 v[172:175], v227
	ds_read_b128 v[176:179], v227 offset:1024
	ds_read_b128 v[180:183], v227 offset:2048
	ds_read_b128 v[184:187], v227 offset:3072
	s_add_u32 s0, s40, 0x100000
	s_addc_u32 s1, s41, 0
	s_mov_b32 m0, s44
	ds_read_b128 v[188:191], v154 offset:32768
	ds_read_b128 v[192:195], v154 offset:33792
	ds_read_b128 v[196:199], v154 offset:34816
	ds_read_b128 v[200:203], v154 offset:35840
	ds_read_b128 v[204:207], v154 offset:36864
	ds_read_b128 v[208:211], v154 offset:37888
	ds_read_b128 v[212:215], v154 offset:38912
	global_load_lds_dwordx4 v128, s[0:1]
	s_mov_b32 m0, s45
	ds_read_b128 v[216:219], v154 offset:39936
	global_load_lds_dwordx4 v132, s[0:1]
	s_waitcnt vmcnt(8) lgkmcnt(0)
	s_setprio 3
	s_barrier
	v_mfma_f32_16x16x32_bf16 v[124:127], v[156:159], v[188:191], v[124:127]
	v_mfma_f32_16x16x32_bf16 v[120:123], v[164:167], v[188:191], v[120:123]
	v_mfma_f32_16x16x32_bf16 v[108:111], v[156:159], v[196:199], v[108:111]
	v_mfma_f32_16x16x32_bf16 v[104:107], v[164:167], v[196:199], v[104:107]
	v_mfma_f32_16x16x32_bf16 v[92:95], v[156:159], v[204:207], v[92:95]
	v_mfma_f32_16x16x32_bf16 v[88:91], v[164:167], v[204:207], v[88:91]
	v_mfma_f32_16x16x32_bf16 v[76:79], v[156:159], v[212:215], v[76:79]
	v_mfma_f32_16x16x32_bf16 v[72:75], v[164:167], v[212:215], v[72:75]
	v_mfma_f32_16x16x32_bf16 v[124:127], v[160:163], v[192:195], v[124:127]
	v_mfma_f32_16x16x32_bf16 v[120:123], v[168:171], v[192:195], v[120:123]
	v_mfma_f32_16x16x32_bf16 v[108:111], v[160:163], v[200:203], v[108:111]
	v_mfma_f32_16x16x32_bf16 v[104:107], v[168:171], v[200:203], v[104:107]
	v_mfma_f32_16x16x32_bf16 v[92:95], v[160:163], v[208:211], v[92:95]
	v_mfma_f32_16x16x32_bf16 v[88:91], v[168:171], v[208:211], v[88:91]
	v_mfma_f32_16x16x32_bf16 v[76:79], v[160:163], v[216:219], v[76:79]
	v_mfma_f32_16x16x32_bf16 v[72:75], v[168:171], v[216:219], v[72:75]
	v_mfma_f32_16x16x32_bf16 v[116:119], v[172:175], v[188:191], v[116:119]
	v_mfma_f32_16x16x32_bf16 v[112:115], v[180:183], v[188:191], v[112:115]
	v_mfma_f32_16x16x32_bf16 v[100:103], v[172:175], v[196:199], v[100:103]
	v_mfma_f32_16x16x32_bf16 v[96:99], v[180:183], v[196:199], v[96:99]
	v_mfma_f32_16x16x32_bf16 v[84:87], v[172:175], v[204:207], v[84:87]
	v_mfma_f32_16x16x32_bf16 v[80:83], v[180:183], v[204:207], v[80:83]
	v_mfma_f32_16x16x32_bf16 v[68:71], v[172:175], v[212:215], v[68:71]
	v_mfma_f32_16x16x32_bf16 v[64:67], v[180:183], v[212:215], v[64:67]
	v_mfma_f32_16x16x32_bf16 v[116:119], v[176:179], v[192:195], v[116:119]
	v_mfma_f32_16x16x32_bf16 v[112:115], v[184:187], v[192:195], v[112:115]
	v_mfma_f32_16x16x32_bf16 v[100:103], v[176:179], v[200:203], v[100:103]
	v_mfma_f32_16x16x32_bf16 v[96:99], v[184:187], v[200:203], v[96:99]
	v_mfma_f32_16x16x32_bf16 v[84:87], v[176:179], v[208:211], v[84:87]
	v_mfma_f32_16x16x32_bf16 v[80:83], v[184:187], v[208:211], v[80:83]
	v_mfma_f32_16x16x32_bf16 v[68:71], v[176:179], v[216:219], v[68:71]
	v_mfma_f32_16x16x32_bf16 v[64:67], v[184:187], v[216:219], v[64:67]
	s_barrier
	s_setprio 0
	s_add_i32 s0, s62, s43
	s_add_u32 s100, s38, 0x80
	s_addc_u32 s101, s39, 0
	s_mov_b32 m0, s0
	ds_read_b128 v[188:191], v154 offset:49152
	ds_read_b128 v[192:195], v154 offset:50176
	ds_read_b128 v[196:199], v154 offset:51200
	ds_read_b128 v[200:203], v154 offset:52224
	global_load_lds_dwordx4 v130, s[100:101]
	s_add_i32 m0, s0, 0x2000
	s_add_u32 s0, s38, 0x100080
	s_addc_u32 s1, s39, 0
	s_add_i32 s38, s63, s43
	global_load_lds_dwordx4 v134, s[100:101]
	s_mov_b32 m0, s38
	ds_read_b128 v[216:219], v154 offset:56320
	global_load_lds_dwordx4 v130, s[0:1]
	s_add_i32 m0, s38, 0x2000
	ds_read_b128 v[212:215], v154 offset:55296
	global_load_lds_dwordx4 v134, s[0:1]
	s_add_u32 s100, s40, 0x80
	s_addc_u32 s101, s41, 0
	s_mov_b32 m0, s46
	ds_read_b128 v[208:211], v154 offset:54272
	global_load_lds_dwordx4 v128, s[100:101]
	s_mov_b32 m0, s47
	ds_read_b128 v[204:207], v154 offset:53248
	global_load_lds_dwordx4 v132, s[100:101]
	s_waitcnt vmcnt(8) lgkmcnt(0)
	s_setprio 3
	s_barrier
	v_mfma_f32_16x16x32_bf16 v[60:63], v[156:159], v[188:191], v[60:63]
	v_mfma_f32_16x16x32_bf16 v[56:59], v[164:167], v[188:191], v[56:59]
	v_mfma_f32_16x16x32_bf16 v[44:47], v[156:159], v[196:199], v[44:47]
	v_mfma_f32_16x16x32_bf16 v[40:43], v[164:167], v[196:199], v[40:43]
	v_mfma_f32_16x16x32_bf16 v[28:31], v[156:159], v[204:207], v[28:31]
	v_mfma_f32_16x16x32_bf16 v[24:27], v[164:167], v[204:207], v[24:27]
	v_mfma_f32_16x16x32_bf16 v[12:15], v[156:159], v[212:215], v[12:15]
	v_mfma_f32_16x16x32_bf16 v[8:11], v[164:167], v[212:215], v[8:11]
	v_mfma_f32_16x16x32_bf16 v[60:63], v[160:163], v[192:195], v[60:63]
	v_mfma_f32_16x16x32_bf16 v[56:59], v[168:171], v[192:195], v[56:59]
	v_mfma_f32_16x16x32_bf16 v[44:47], v[160:163], v[200:203], v[44:47]
	v_mfma_f32_16x16x32_bf16 v[40:43], v[168:171], v[200:203], v[40:43]
	v_mfma_f32_16x16x32_bf16 v[28:31], v[160:163], v[208:211], v[28:31]
	v_mfma_f32_16x16x32_bf16 v[24:27], v[168:171], v[208:211], v[24:27]
	v_mfma_f32_16x16x32_bf16 v[12:15], v[160:163], v[216:219], v[12:15]
	v_mfma_f32_16x16x32_bf16 v[8:11], v[168:171], v[216:219], v[8:11]
	v_mfma_f32_16x16x32_bf16 v[52:55], v[172:175], v[188:191], v[52:55]
	v_mfma_f32_16x16x32_bf16 v[48:51], v[180:183], v[188:191], v[48:51]
	v_mfma_f32_16x16x32_bf16 v[36:39], v[172:175], v[196:199], v[36:39]
	v_mfma_f32_16x16x32_bf16 v[32:35], v[180:183], v[196:199], v[32:35]
	v_mfma_f32_16x16x32_bf16 v[20:23], v[172:175], v[204:207], v[20:23]
	v_mfma_f32_16x16x32_bf16 v[16:19], v[180:183], v[204:207], v[16:19]
	v_mfma_f32_16x16x32_bf16 v[4:7], v[172:175], v[212:215], v[4:7]
	v_mfma_f32_16x16x32_bf16 v[0:3], v[180:183], v[212:215], v[0:3]
	v_mfma_f32_16x16x32_bf16 v[52:55], v[176:179], v[192:195], v[52:55]
	v_mfma_f32_16x16x32_bf16 v[48:51], v[184:187], v[192:195], v[48:51]
	v_mfma_f32_16x16x32_bf16 v[36:39], v[176:179], v[200:203], v[36:39]
	v_mfma_f32_16x16x32_bf16 v[32:35], v[184:187], v[200:203], v[32:35]
	v_mfma_f32_16x16x32_bf16 v[20:23], v[176:179], v[208:211], v[20:23]
	v_mfma_f32_16x16x32_bf16 v[16:19], v[184:187], v[208:211], v[16:19]
	v_mfma_f32_16x16x32_bf16 v[4:7], v[176:179], v[216:219], v[4:7]
	v_mfma_f32_16x16x32_bf16 v[0:3], v[184:187], v[216:219], v[0:3]
	s_barrier
	s_setprio 0
	s_add_u32 s36, s36, 0x100
	s_addc_u32 s37, s37, 0
	s_add_i32 s61, s61, 2
	s_add_u32 s59, s59, 0x100
	s_addc_u32 s60, s60, 0
	s_cmp_gt_u32 s61, 61
	s_cbranch_scc0 .LBB0_677
	s_and_b64 vcc, exec, s[12:13]
	s_cbranch_vccz .LBB0_680
	s_barrier

.LBB0_705:
	ds_read_b128 v[24:27], v191
	ds_read_b128 v[28:31], v191 offset:1024
	ds_read_b128 v[16:19], v191 offset:2048
	ds_read_b128 v[20:23], v191 offset:3072
	ds_read_b128 v[8:11], v192
	ds_read_b128 v[12:15], v192 offset:1024
	ds_read_b128 v[0:3], v192 offset:2048
	ds_read_b128 v[4:7], v192 offset:3072
	s_add_u32 s0, s44, 0xfff80080
	s_addc_u32 s1, s45, -1
	s_cmp_eq_u32 s70, 28
	s_cselect_b32 s49, s60, s1
	s_cselect_b32 s48, s66, s0
	s_cselect_b32 s47, s31, s69
	s_cselect_b32 s46, s67, s68
	s_add_i32 m0, s41, 0xc000
	ds_read_b128 v[178:181], v193
	ds_read_b128 v[182:185], v193 offset:1024
	ds_read_b128 v[194:197], v193 offset:2048
	ds_read_b128 v[198:201], v193 offset:3072
	ds_read_b128 v[208:211], v193 offset:4096
	ds_read_b128 v[212:215], v193 offset:5120
	ds_read_b128 v[216:219], v193 offset:6144
	global_load_lds_dwordx4 v170, s[44:45]
	s_add_i32 m0, s41, 0xe000
	ds_read_b128 v[220:223], v193 offset:7168
	global_load_lds_dwordx4 v172, s[44:45]
	s_waitcnt vmcnt(8) lgkmcnt(0)
	s_setprio 3
	s_barrier
	v_mfma_scale_f32_16x16x128_f8f6f4 v[156:159], v[24:31], v[178:185], v[156:159], v186, v186 op_sel_hi:[0,0,0]
	v_mfma_scale_f32_16x16x128_f8f6f4 v[152:155], v[16:23], v[178:185], v[152:155], v186, v186 op_sel_hi:[0,0,0]
	v_mfma_scale_f32_16x16x128_f8f6f4 v[140:143], v[24:31], v[194:201], v[140:143], v186, v186 op_sel_hi:[0,0,0]
	v_mfma_scale_f32_16x16x128_f8f6f4 v[136:139], v[16:23], v[194:201], v[136:139], v186, v186 op_sel_hi:[0,0,0]
	v_mfma_scale_f32_16x16x128_f8f6f4 v[124:127], v[24:31], v[208:215], v[124:127], v186, v186 op_sel_hi:[0,0,0]
	v_mfma_scale_f32_16x16x128_f8f6f4 v[120:123], v[16:23], v[208:215], v[120:123], v186, v186 op_sel_hi:[0,0,0]
	v_mfma_scale_f32_16x16x128_f8f6f4 v[108:111], v[24:31], v[216:223], v[108:111], v186, v186 op_sel_hi:[0,0,0]
	v_mfma_scale_f32_16x16x128_f8f6f4 v[104:107], v[16:23], v[216:223], v[104:107], v186, v186 op_sel_hi:[0,0,0]
	v_mfma_scale_f32_16x16x128_f8f6f4 v[148:151], v[8:15], v[178:185], v[148:151], v186, v186 op_sel_hi:[0,0,0]
	v_mfma_scale_f32_16x16x128_f8f6f4 v[144:147], v[0:7], v[178:185], v[144:147], v186, v186 op_sel_hi:[0,0,0]
	v_mfma_scale_f32_16x16x128_f8f6f4 v[132:135], v[8:15], v[194:201], v[132:135], v186, v186 op_sel_hi:[0,0,0]
	v_mfma_scale_f32_16x16x128_f8f6f4 v[128:131], v[0:7], v[194:201], v[128:131], v186, v186 op_sel_hi:[0,0,0]
	v_mfma_scale_f32_16x16x128_f8f6f4 v[116:119], v[8:15], v[208:215], v[116:119], v186, v186 op_sel_hi:[0,0,0]
	v_mfma_scale_f32_16x16x128_f8f6f4 v[112:115], v[0:7], v[208:215], v[112:115], v186, v186 op_sel_hi:[0,0,0]
	v_mfma_scale_f32_16x16x128_f8f6f4 v[100:103], v[8:15], v[216:223], v[100:103], v186, v186 op_sel_hi:[0,0,0]
	v_mfma_scale_f32_16x16x128_f8f6f4 v[96:99], v[0:7], v[216:223], v[96:99], v186, v186 op_sel_hi:[0,0,0]
	s_barrier
	s_setprio 0
	s_add_i32 s0, s58, s51
	s_mov_b32 m0, s0
	ds_read_b128 v[194:197], v193 offset:16384
	ds_read_b128 v[198:201], v193 offset:17408
	ds_read_b128 v[208:211], v193 offset:18432
	ds_read_b128 v[212:215], v193 offset:19456
	ds_read_b128 v[216:219], v193 offset:20480
	global_load_lds_dwordx4 v162, s[46:47]
	s_add_i32 m0, s0, 0x2000
	s_add_u32 s0, s46, 0x80000
	s_addc_u32 s1, s47, 0
	s_add_i32 s71, s59, s51
	global_load_lds_dwordx4 v166, s[46:47]
	s_mov_b32 m0, s71
	s_nop 0
	global_load_lds_dwordx4 v162, s[0:1]
	s_add_i32 m0, s71, 0x2000
	ds_read_b128 v[228:231], v193 offset:23552
	global_load_lds_dwordx4 v166, s[0:1]
	s_mov_b32 m0, s41
	ds_read_b128 v[224:227], v193 offset:22528
	global_load_lds_dwordx4 v160, s[48:49]
	s_mov_b32 m0, s43
	ds_read_b128 v[220:223], v193 offset:21504
	global_load_lds_dwordx4 v164, s[48:49]
	s_waitcnt vmcnt(8) lgkmcnt(0)
	s_setprio 3
	s_barrier
	v_mfma_scale_f32_16x16x128_f8f6f4 v[92:95], v[24:31], v[194:201], v[92:95], v186, v186 op_sel_hi:[0,0,0]
	v_mfma_scale_f32_16x16x128_f8f6f4 v[88:91], v[16:23], v[194:201], v[88:91], v186, v186 op_sel_hi:[0,0,0]
	v_mfma_scale_f32_16x16x128_f8f6f4 v[80:83], v[24:31], v[208:215], v[80:83], v186, v186 op_sel_hi:[0,0,0]
	v_mfma_scale_f32_16x16x128_f8f6f4 v[72:75], v[16:23], v[208:215], v[72:75], v186, v186 op_sel_hi:[0,0,0]
	v_mfma_scale_f32_16x16x128_f8f6f4 v[64:67], v[24:31], v[216:223], v[64:67], v186, v186 op_sel_hi:[0,0,0]
	v_mfma_scale_f32_16x16x128_f8f6f4 v[56:59], v[16:23], v[216:223], v[56:59], v186, v186 op_sel_hi:[0,0,0]
	v_mfma_scale_f32_16x16x128_f8f6f4 v[48:51], v[24:31], v[224:231], v[48:51], v186, v186 op_sel_hi:[0,0,0]
	v_mfma_scale_f32_16x16x128_f8f6f4 v[40:43], v[16:23], v[224:231], v[40:43], v186, v186 op_sel_hi:[0,0,0]
	v_mfma_scale_f32_16x16x128_f8f6f4 v[84:87], v[8:15], v[194:201], v[84:87], v186, v186 op_sel_hi:[0,0,0]
	v_mfma_scale_f32_16x16x128_f8f6f4 v[76:79], v[0:7], v[194:201], v[76:79], v186, v186 op_sel_hi:[0,0,0]
	v_mfma_scale_f32_16x16x128_f8f6f4 v[68:71], v[8:15], v[208:215], v[68:71], v186, v186 op_sel_hi:[0,0,0]
	v_mfma_scale_f32_16x16x128_f8f6f4 v[60:63], v[0:7], v[208:215], v[60:63], v186, v186 op_sel_hi:[0,0,0]
	v_mfma_scale_f32_16x16x128_f8f6f4 v[52:55], v[8:15], v[216:223], v[52:55], v186, v186 op_sel_hi:[0,0,0]
	v_mfma_scale_f32_16x16x128_f8f6f4 v[44:47], v[0:7], v[216:223], v[44:47], v186, v186 op_sel_hi:[0,0,0]
	v_mfma_scale_f32_16x16x128_f8f6f4 v[36:39], v[8:15], v[224:231], v[36:39], v186, v186 op_sel_hi:[0,0,0]
	v_mfma_scale_f32_16x16x128_f8f6f4 v[32:35], v[0:7], v[224:231], v[32:35], v186, v186 op_sel_hi:[0,0,0]
	s_barrier
	s_setprio 0
	s_add_i32 s71, 0, 0x18000
	s_add_i32 s73, 0, 0x1c000
	ds_read_b128 v[0:3], v202
	ds_read_b128 v[4:7], v202 offset:1024
	ds_read_b128 v[8:11], v202 offset:2048
	ds_read_b128 v[12:15], v202 offset:3072
	ds_read_b128 v[16:19], v203
	ds_read_b128 v[20:23], v203 offset:1024
	ds_read_b128 v[24:27], v203 offset:2048
	ds_read_b128 v[28:31], v203 offset:3072
	s_add_u32 s0, s48, 0x80000
	s_addc_u32 s1, s49, 0
	s_mov_b32 m0, s52
	ds_read_b128 v[194:197], v193 offset:32768
	ds_read_b128 v[198:201], v193 offset:33792
	ds_read_b128 v[208:211], v193 offset:34816
	ds_read_b128 v[212:215], v193 offset:35840
	ds_read_b128 v[216:219], v193 offset:36864
	ds_read_b128 v[220:223], v193 offset:37888
	ds_read_b128 v[224:227], v193 offset:38912
	global_load_lds_dwordx4 v160, s[0:1]
	s_mov_b32 m0, s53
	ds_read_b128 v[228:231], v193 offset:39936
	global_load_lds_dwordx4 v164, s[0:1]
	s_waitcnt vmcnt(8) lgkmcnt(0)
	s_setprio 3
	s_barrier
	v_mfma_scale_f32_16x16x128_f8f6f4 v[156:159], v[0:7], v[194:201], v[156:159], v186, v186 op_sel_hi:[0,0,0]
	v_mfma_scale_f32_16x16x128_f8f6f4 v[152:155], v[8:15], v[194:201], v[152:155], v186, v186 op_sel_hi:[0,0,0]
	v_mfma_scale_f32_16x16x128_f8f6f4 v[140:143], v[0:7], v[208:215], v[140:143], v186, v186 op_sel_hi:[0,0,0]
	v_mfma_scale_f32_16x16x128_f8f6f4 v[136:139], v[8:15], v[208:215], v[136:139], v186, v186 op_sel_hi:[0,0,0]
	v_mfma_scale_f32_16x16x128_f8f6f4 v[124:127], v[0:7], v[216:223], v[124:127], v186, v186 op_sel_hi:[0,0,0]
	v_mfma_scale_f32_16x16x128_f8f6f4 v[120:123], v[8:15], v[216:223], v[120:123], v186, v186 op_sel_hi:[0,0,0]
	v_mfma_scale_f32_16x16x128_f8f6f4 v[108:111], v[0:7], v[224:231], v[108:111], v186, v186 op_sel_hi:[0,0,0]
	v_mfma_scale_f32_16x16x128_f8f6f4 v[104:107], v[8:15], v[224:231], v[104:107], v186, v186 op_sel_hi:[0,0,0]
	v_mfma_scale_f32_16x16x128_f8f6f4 v[148:151], v[16:23], v[194:201], v[148:151], v186, v186 op_sel_hi:[0,0,0]
	v_mfma_scale_f32_16x16x128_f8f6f4 v[144:147], v[24:31], v[194:201], v[144:147], v186, v186 op_sel_hi:[0,0,0]
	v_mfma_scale_f32_16x16x128_f8f6f4 v[132:135], v[16:23], v[208:215], v[132:135], v186, v186 op_sel_hi:[0,0,0]
	v_mfma_scale_f32_16x16x128_f8f6f4 v[128:131], v[24:31], v[208:215], v[128:131], v186, v186 op_sel_hi:[0,0,0]
	v_mfma_scale_f32_16x16x128_f8f6f4 v[116:119], v[16:23], v[216:223], v[116:119], v186, v186 op_sel_hi:[0,0,0]
	v_mfma_scale_f32_16x16x128_f8f6f4 v[112:115], v[24:31], v[216:223], v[112:115], v186, v186 op_sel_hi:[0,0,0]
	v_mfma_scale_f32_16x16x128_f8f6f4 v[100:103], v[16:23], v[224:231], v[100:103], v186, v186 op_sel_hi:[0,0,0]
	v_mfma_scale_f32_16x16x128_f8f6f4 v[96:99], v[24:31], v[224:231], v[96:99], v186, v186 op_sel_hi:[0,0,0]
	s_barrier
	s_setprio 0
	s_add_i32 s0, s71, s51
	s_add_u32 s100, s46, 0x80
	s_addc_u32 s101, s47, 0
	s_mov_b32 m0, s0
	ds_read_b128 v[194:197], v193 offset:49152
	ds_read_b128 v[198:201], v193 offset:50176
	ds_read_b128 v[208:211], v193 offset:51200
	ds_read_b128 v[212:215], v193 offset:52224
	global_load_lds_dwordx4 v162, s[100:101]
	s_add_i32 m0, s0, 0x2000
	s_add_u32 s0, s46, 0x80080
	s_addc_u32 s1, s47, 0
	s_add_i32 s46, s73, s51
	global_load_lds_dwordx4 v166, s[100:101]
	s_mov_b32 m0, s46
	ds_read_b128 v[228:231], v193 offset:56320
	global_load_lds_dwordx4 v162, s[0:1]
	s_add_i32 m0, s46, 0x2000
	ds_read_b128 v[224:227], v193 offset:55296
	global_load_lds_dwordx4 v166, s[0:1]
	s_add_u32 s100, s48, 0x80
	s_addc_u32 s101, s49, 0
	s_mov_b32 m0, s55
	ds_read_b128 v[220:223], v193 offset:54272
	global_load_lds_dwordx4 v160, s[100:101]
	s_mov_b32 m0, s56
	ds_read_b128 v[216:219], v193 offset:53248
	global_load_lds_dwordx4 v164, s[100:101]
	s_waitcnt vmcnt(8) lgkmcnt(0)
	s_setprio 3
	s_barrier
	v_mfma_scale_f32_16x16x128_f8f6f4 v[92:95], v[0:7], v[194:201], v[92:95], v186, v186 op_sel_hi:[0,0,0]
	v_mfma_scale_f32_16x16x128_f8f6f4 v[88:91], v[8:15], v[194:201], v[88:91], v186, v186 op_sel_hi:[0,0,0]
	v_mfma_scale_f32_16x16x128_f8f6f4 v[80:83], v[0:7], v[208:215], v[80:83], v186, v186 op_sel_hi:[0,0,0]
	v_mfma_scale_f32_16x16x128_f8f6f4 v[72:75], v[8:15], v[208:215], v[72:75], v186, v186 op_sel_hi:[0,0,0]
	v_mfma_scale_f32_16x16x128_f8f6f4 v[64:67], v[0:7], v[216:223], v[64:67], v186, v186 op_sel_hi:[0,0,0]
	v_mfma_scale_f32_16x16x128_f8f6f4 v[56:59], v[8:15], v[216:223], v[56:59], v186, v186 op_sel_hi:[0,0,0]
	v_mfma_scale_f32_16x16x128_f8f6f4 v[48:51], v[0:7], v[224:231], v[48:51], v186, v186 op_sel_hi:[0,0,0]
	v_mfma_scale_f32_16x16x128_f8f6f4 v[40:43], v[8:15], v[224:231], v[40:43], v186, v186 op_sel_hi:[0,0,0]
	v_mfma_scale_f32_16x16x128_f8f6f4 v[84:87], v[16:23], v[194:201], v[84:87], v186, v186 op_sel_hi:[0,0,0]
	v_mfma_scale_f32_16x16x128_f8f6f4 v[76:79], v[24:31], v[194:201], v[76:79], v186, v186 op_sel_hi:[0,0,0]
	v_mfma_scale_f32_16x16x128_f8f6f4 v[68:71], v[16:23], v[208:215], v[68:71], v186, v186 op_sel_hi:[0,0,0]
	v_mfma_scale_f32_16x16x128_f8f6f4 v[60:63], v[24:31], v[208:215], v[60:63], v186, v186 op_sel_hi:[0,0,0]
	v_mfma_scale_f32_16x16x128_f8f6f4 v[52:55], v[16:23], v[216:223], v[52:55], v186, v186 op_sel_hi:[0,0,0]
	v_mfma_scale_f32_16x16x128_f8f6f4 v[44:47], v[24:31], v[216:223], v[44:47], v186, v186 op_sel_hi:[0,0,0]
	v_mfma_scale_f32_16x16x128_f8f6f4 v[36:39], v[16:23], v[224:231], v[36:39], v186, v186 op_sel_hi:[0,0,0]
	v_mfma_scale_f32_16x16x128_f8f6f4 v[32:35], v[24:31], v[224:231], v[32:35], v186, v186 op_sel_hi:[0,0,0]
	s_barrier
	s_setprio 0
	s_add_u32 s44, s44, 0x100
	s_addc_u32 s45, s45, 0
	s_add_i32 s70, s70, 2
	s_add_u32 s68, s68, 0x100
	s_addc_u32 s69, s69, 0
	s_cmp_gt_u32 s70, 29
	s_cbranch_scc0 .LBB0_705
	s_and_b64 vcc, exec, s[12:13]
	s_cbranch_vccz .LBB0_708
	s_barrier

.LBB0_1544:
	v_add_u32_e32 v1, s88, v155
	ds_read_b128 v[158:161], v1
	ds_read_b128 v[162:165], v1 offset:1024
	ds_read_b128 v[166:169], v1 offset:2048
	ds_read_b128 v[170:173], v1 offset:3072
	v_add_u32_e32 v1, s89, v155
	s_add_u32 s0, s50, s6
	ds_read_b128 v[174:177], v1
	ds_read_b128 v[178:181], v1 offset:1024
	ds_read_b128 v[182:185], v1 offset:2048
	ds_read_b128 v[186:189], v1 offset:3072
	s_addc_u32 s1, s51, s7
	s_add_u32 s0, s0, 0x100
	s_addc_u32 s1, s1, 0
	s_add_u32 s26, s96, s6
	s_addc_u32 s27, s97, s7
	s_cmpk_eq_i32 s6, 0x1f00
	s_cselect_b32 s55, s47, s1
	s_cselect_b32 s54, s46, s0
	s_cselect_b32 s53, s92, s27
	s_cselect_b32 s52, s93, s26
	v_lshl_add_u64 v[2:3], v[148:149], 0, s[6:7]
	s_add_i32 m0, s61, 0xc000
	ds_read_b128 v[190:193], v157
	ds_read_b128 v[194:197], v157 offset:1024
	ds_read_b128 v[198:201], v157 offset:2048
	ds_read_b128 v[210:213], v157 offset:3072
	ds_read_b128 v[214:217], v157 offset:4096
	ds_read_b128 v[218:221], v157 offset:5120
	ds_read_b128 v[222:225], v157 offset:6144
	global_load_lds_dwordx4 v[2:3], off
	v_lshl_add_u64 v[2:3], v[150:151], 0, s[6:7]
	s_add_i32 m0, s61, 0xe000
	ds_read_b128 v[226:229], v157 offset:7168
	global_load_lds_dwordx4 v[2:3], off
	s_waitcnt vmcnt(8) lgkmcnt(0)
	s_setprio 3
	s_barrier
	v_mfma_f32_16x16x32_bf16 v[128:131], v[158:161], v[190:193], v[128:131]
	v_mfma_f32_16x16x32_bf16 v[124:127], v[166:169], v[190:193], v[124:127]
	v_mfma_f32_16x16x32_bf16 v[112:115], v[158:161], v[198:201], v[112:115]
	v_mfma_f32_16x16x32_bf16 v[108:111], v[166:169], v[198:201], v[108:111]
	v_mfma_f32_16x16x32_bf16 v[96:99], v[158:161], v[214:217], v[96:99]
	v_mfma_f32_16x16x32_bf16 v[92:95], v[166:169], v[214:217], v[92:95]
	v_mfma_f32_16x16x32_bf16 v[80:83], v[158:161], v[222:225], v[80:83]
	v_mfma_f32_16x16x32_bf16 v[76:79], v[166:169], v[222:225], v[76:79]
	v_mfma_f32_16x16x32_bf16 v[128:131], v[162:165], v[194:197], v[128:131]
	v_mfma_f32_16x16x32_bf16 v[124:127], v[170:173], v[194:197], v[124:127]
	v_mfma_f32_16x16x32_bf16 v[112:115], v[162:165], v[210:213], v[112:115]
	v_mfma_f32_16x16x32_bf16 v[108:111], v[170:173], v[210:213], v[108:111]
	v_mfma_f32_16x16x32_bf16 v[96:99], v[162:165], v[218:221], v[96:99]
	v_mfma_f32_16x16x32_bf16 v[92:95], v[170:173], v[218:221], v[92:95]
	v_mfma_f32_16x16x32_bf16 v[80:83], v[162:165], v[226:229], v[80:83]
	v_mfma_f32_16x16x32_bf16 v[76:79], v[170:173], v[226:229], v[76:79]
	v_mfma_f32_16x16x32_bf16 v[120:123], v[174:177], v[190:193], v[120:123]
	v_mfma_f32_16x16x32_bf16 v[116:119], v[182:185], v[190:193], v[116:119]
	v_mfma_f32_16x16x32_bf16 v[104:107], v[174:177], v[198:201], v[104:107]
	v_mfma_f32_16x16x32_bf16 v[100:103], v[182:185], v[198:201], v[100:103]
	v_mfma_f32_16x16x32_bf16 v[88:91], v[174:177], v[214:217], v[88:91]
	v_mfma_f32_16x16x32_bf16 v[84:87], v[182:185], v[214:217], v[84:87]
	v_mfma_f32_16x16x32_bf16 v[72:75], v[174:177], v[222:225], v[72:75]
	v_mfma_f32_16x16x32_bf16 v[68:71], v[182:185], v[222:225], v[68:71]
	v_mfma_f32_16x16x32_bf16 v[120:123], v[178:181], v[194:197], v[120:123]
	v_mfma_f32_16x16x32_bf16 v[116:119], v[186:189], v[194:197], v[116:119]
	v_mfma_f32_16x16x32_bf16 v[104:107], v[178:181], v[210:213], v[104:107]
	v_mfma_f32_16x16x32_bf16 v[100:103], v[186:189], v[210:213], v[100:103]
	v_mfma_f32_16x16x32_bf16 v[88:91], v[178:181], v[218:221], v[88:91]
	v_mfma_f32_16x16x32_bf16 v[84:87], v[186:189], v[218:221], v[84:87]
	v_mfma_f32_16x16x32_bf16 v[72:75], v[178:181], v[226:229], v[72:75]
	v_mfma_f32_16x16x32_bf16 v[68:71], v[186:189], v[226:229], v[68:71]
	s_barrier
	s_setprio 0
	s_add_i32 s0, s88, s60
	v_lshl_add_u64 v[202:203], s[52:53], 0, v[134:135]
	s_mov_b32 m0, s0
	ds_read_b128 v[190:193], v157 offset:16384
	ds_read_b128 v[194:197], v157 offset:17408
	ds_read_b128 v[198:201], v157 offset:18432
	ds_read_b128 v[210:213], v157 offset:19456
	ds_read_b128 v[214:217], v157 offset:20480
	ds_read_b128 v[218:221], v157 offset:21504
	global_load_lds_dwordx4 v[202:203], off
	s_add_i32 m0, s0, 0x2000
	s_add_u32 s0, s52, 0x100000
	v_lshl_add_u64 v[230:231], s[52:53], 0, v[138:139]
	s_addc_u32 s1, s53, 0
	s_add_i32 s26, s89, s60
	global_load_lds_dwordx4 v[230:231], off
	s_mov_b32 m0, s26
	v_lshl_add_u64 v[232:233], s[54:55], 0, v[132:133]
	global_load_lds_dwordx4 v134, s[0:1]
	s_add_i32 m0, s26, 0x2000
	v_lshl_add_u64 v[234:235], s[54:55], 0, v[136:137]
	global_load_lds_dwordx4 v138, s[0:1]
	s_mov_b32 m0, s61
	ds_read_b128 v[226:229], v157 offset:23552
	global_load_lds_dwordx4 v[232:233], off
	s_mov_b32 m0, s62
	ds_read_b128 v[222:225], v157 offset:22528
	global_load_lds_dwordx4 v[234:235], off
	s_waitcnt vmcnt(8) lgkmcnt(0)
	s_setprio 3
	s_barrier
	v_mfma_f32_16x16x32_bf16 v[64:67], v[158:161], v[190:193], v[64:67]
	v_mfma_f32_16x16x32_bf16 v[60:63], v[166:169], v[190:193], v[60:63]
	v_mfma_f32_16x16x32_bf16 v[48:51], v[158:161], v[198:201], v[48:51]
	v_mfma_f32_16x16x32_bf16 v[44:47], v[166:169], v[198:201], v[44:47]
	v_mfma_f32_16x16x32_bf16 v[32:35], v[158:161], v[214:217], v[32:35]
	v_mfma_f32_16x16x32_bf16 v[28:31], v[166:169], v[214:217], v[28:31]
	v_mfma_f32_16x16x32_bf16 v[16:19], v[158:161], v[222:225], v[16:19]
	v_mfma_f32_16x16x32_bf16 v[12:15], v[166:169], v[222:225], v[12:15]
	v_mfma_f32_16x16x32_bf16 v[64:67], v[162:165], v[194:197], v[64:67]
	v_mfma_f32_16x16x32_bf16 v[60:63], v[170:173], v[194:197], v[60:63]
	v_mfma_f32_16x16x32_bf16 v[48:51], v[162:165], v[210:213], v[48:51]
	v_mfma_f32_16x16x32_bf16 v[44:47], v[170:173], v[210:213], v[44:47]
	v_mfma_f32_16x16x32_bf16 v[32:35], v[162:165], v[218:221], v[32:35]
	v_mfma_f32_16x16x32_bf16 v[28:31], v[170:173], v[218:221], v[28:31]
	v_mfma_f32_16x16x32_bf16 v[16:19], v[162:165], v[226:229], v[16:19]
	v_mfma_f32_16x16x32_bf16 v[12:15], v[170:173], v[226:229], v[12:15]
	v_mfma_f32_16x16x32_bf16 v[56:59], v[174:177], v[190:193], v[56:59]
	v_mfma_f32_16x16x32_bf16 v[52:55], v[182:185], v[190:193], v[52:55]
	v_mfma_f32_16x16x32_bf16 v[40:43], v[174:177], v[198:201], v[40:43]
	v_mfma_f32_16x16x32_bf16 v[36:39], v[182:185], v[198:201], v[36:39]
	v_mfma_f32_16x16x32_bf16 v[24:27], v[174:177], v[214:217], v[24:27]
	v_mfma_f32_16x16x32_bf16 v[20:23], v[182:185], v[214:217], v[20:23]
	v_mfma_f32_16x16x32_bf16 v[8:11], v[174:177], v[222:225], v[8:11]
	v_mfma_f32_16x16x32_bf16 v[2:5], v[182:185], v[222:225], v[4:7]
	v_mfma_f32_16x16x32_bf16 v[56:59], v[178:181], v[194:197], v[56:59]
	v_mfma_f32_16x16x32_bf16 v[52:55], v[186:189], v[194:197], v[52:55]
	v_mfma_f32_16x16x32_bf16 v[40:43], v[178:181], v[210:213], v[40:43]
	v_mfma_f32_16x16x32_bf16 v[36:39], v[186:189], v[210:213], v[36:39]
	v_mfma_f32_16x16x32_bf16 v[24:27], v[178:181], v[218:221], v[24:27]
	v_mfma_f32_16x16x32_bf16 v[20:23], v[186:189], v[218:221], v[20:23]
	v_mfma_f32_16x16x32_bf16 v[8:11], v[178:181], v[226:229], v[8:11]
	v_mfma_f32_16x16x32_bf16 v[2:5], v[186:189], v[226:229], v[2:5]
	s_barrier
	s_setprio 0
	s_add_i32 s26, 0, 0x18000
	v_add_u32_e32 v1, s26, v155
	s_add_i32 s27, 0, 0x1c000
	ds_read_b128 v[158:161], v1
	ds_read_b128 v[162:165], v1 offset:1024
	ds_read_b128 v[166:169], v1 offset:2048
	ds_read_b128 v[170:173], v1 offset:3072
	v_add_u32_e32 v1, s27, v155
	ds_read_b128 v[174:177], v1
	ds_read_b128 v[178:181], v1 offset:1024
	ds_read_b128 v[182:185], v1 offset:2048
	ds_read_b128 v[186:189], v1 offset:3072
	s_add_u32 s0, s54, 0x180000
	s_addc_u32 s1, s55, 0
	s_mov_b32 m0, s63
	ds_read_b128 v[190:193], v157 offset:32768
	ds_read_b128 v[194:197], v157 offset:33792
	ds_read_b128 v[198:201], v157 offset:34816
	ds_read_b128 v[210:213], v157 offset:35840
	ds_read_b128 v[214:217], v157 offset:36864
	ds_read_b128 v[218:221], v157 offset:37888
	ds_read_b128 v[222:225], v157 offset:38912
	global_load_lds_dwordx4 v132, s[0:1]
	s_mov_b32 m0, s64
	ds_read_b128 v[226:229], v157 offset:39936
	global_load_lds_dwordx4 v136, s[0:1]
	s_waitcnt vmcnt(8) lgkmcnt(0)
	s_setprio 3
	s_barrier
	v_mfma_f32_16x16x32_bf16 v[128:131], v[158:161], v[190:193], v[128:131]
	v_mfma_f32_16x16x32_bf16 v[124:127], v[166:169], v[190:193], v[124:127]
	v_mfma_f32_16x16x32_bf16 v[112:115], v[158:161], v[198:201], v[112:115]
	v_mfma_f32_16x16x32_bf16 v[108:111], v[166:169], v[198:201], v[108:111]
	v_mfma_f32_16x16x32_bf16 v[96:99], v[158:161], v[214:217], v[96:99]
	v_mfma_f32_16x16x32_bf16 v[92:95], v[166:169], v[214:217], v[92:95]
	v_mfma_f32_16x16x32_bf16 v[80:83], v[158:161], v[222:225], v[80:83]
	v_mfma_f32_16x16x32_bf16 v[76:79], v[166:169], v[222:225], v[76:79]
	v_mfma_f32_16x16x32_bf16 v[128:131], v[162:165], v[194:197], v[128:131]
	v_mfma_f32_16x16x32_bf16 v[124:127], v[170:173], v[194:197], v[124:127]
	v_mfma_f32_16x16x32_bf16 v[112:115], v[162:165], v[210:213], v[112:115]
	v_mfma_f32_16x16x32_bf16 v[108:111], v[170:173], v[210:213], v[108:111]
	v_mfma_f32_16x16x32_bf16 v[96:99], v[162:165], v[218:221], v[96:99]
	v_mfma_f32_16x16x32_bf16 v[92:95], v[170:173], v[218:221], v[92:95]
	v_mfma_f32_16x16x32_bf16 v[80:83], v[162:165], v[226:229], v[80:83]
	v_mfma_f32_16x16x32_bf16 v[76:79], v[170:173], v[226:229], v[76:79]
	v_mfma_f32_16x16x32_bf16 v[120:123], v[174:177], v[190:193], v[120:123]
	v_mfma_f32_16x16x32_bf16 v[116:119], v[182:185], v[190:193], v[116:119]
	v_mfma_f32_16x16x32_bf16 v[104:107], v[174:177], v[198:201], v[104:107]
	v_mfma_f32_16x16x32_bf16 v[100:103], v[182:185], v[198:201], v[100:103]
	v_mfma_f32_16x16x32_bf16 v[88:91], v[174:177], v[214:217], v[88:91]
	v_mfma_f32_16x16x32_bf16 v[84:87], v[182:185], v[214:217], v[84:87]
	v_mfma_f32_16x16x32_bf16 v[72:75], v[174:177], v[222:225], v[72:75]
	v_mfma_f32_16x16x32_bf16 v[68:71], v[182:185], v[222:225], v[68:71]
	v_mfma_f32_16x16x32_bf16 v[120:123], v[178:181], v[194:197], v[120:123]
	v_mfma_f32_16x16x32_bf16 v[116:119], v[186:189], v[194:197], v[116:119]
	v_mfma_f32_16x16x32_bf16 v[104:107], v[178:181], v[210:213], v[104:107]
	v_mfma_f32_16x16x32_bf16 v[100:103], v[186:189], v[210:213], v[100:103]
	v_mfma_f32_16x16x32_bf16 v[88:91], v[178:181], v[218:221], v[88:91]
	v_mfma_f32_16x16x32_bf16 v[84:87], v[186:189], v[218:221], v[84:87]
	v_mfma_f32_16x16x32_bf16 v[72:75], v[178:181], v[226:229], v[72:75]
	v_mfma_f32_16x16x32_bf16 v[68:71], v[186:189], v[226:229], v[68:71]
	s_barrier
	s_setprio 0
	s_add_i32 s0, s26, s60
	v_lshl_add_u64 v[6:7], v[202:203], 0, s[16:17]
	s_mov_b32 m0, s0
	ds_read_b128 v[190:193], v157 offset:49152
	ds_read_b128 v[194:197], v157 offset:50176
	ds_read_b128 v[198:201], v157 offset:51200
	ds_read_b128 v[210:213], v157 offset:52224
	global_load_lds_dwordx4 v[6:7], off
	s_add_i32 m0, s0, 0x2000
	s_add_u32 s0, s52, 0x100080
	v_lshl_add_u64 v[6:7], v[230:231], 0, s[16:17]
	s_addc_u32 s1, s53, 0
	s_add_i32 s26, s27, s60
	global_load_lds_dwordx4 v[6:7], off
	s_mov_b32 m0, s26
	ds_read_b128 v[226:229], v157 offset:56320
	global_load_lds_dwordx4 v134, s[0:1]
	s_add_i32 m0, s26, 0x2000
	ds_read_b128 v[222:225], v157 offset:55296
	global_load_lds_dwordx4 v138, s[0:1]
	v_lshl_add_u64 v[6:7], v[232:233], 0, s[16:17]
	s_mov_b32 m0, s68
	ds_read_b128 v[218:221], v157 offset:54272
	global_load_lds_dwordx4 v[6:7], off
	v_lshl_add_u64 v[6:7], v[234:235], 0, s[16:17]
	s_mov_b32 m0, s69
	ds_read_b128 v[214:217], v157 offset:53248
	global_load_lds_dwordx4 v[6:7], off
	s_waitcnt vmcnt(8) lgkmcnt(0)
	s_setprio 3
	s_barrier
	v_mfma_f32_16x16x32_bf16 v[64:67], v[158:161], v[190:193], v[64:67]
	v_mfma_f32_16x16x32_bf16 v[60:63], v[166:169], v[190:193], v[60:63]
	v_mfma_f32_16x16x32_bf16 v[48:51], v[158:161], v[198:201], v[48:51]
	v_mfma_f32_16x16x32_bf16 v[44:47], v[166:169], v[198:201], v[44:47]
	v_mfma_f32_16x16x32_bf16 v[32:35], v[158:161], v[214:217], v[32:35]
	v_mfma_f32_16x16x32_bf16 v[28:31], v[166:169], v[214:217], v[28:31]
	v_mfma_f32_16x16x32_bf16 v[16:19], v[158:161], v[222:225], v[16:19]
	v_mfma_f32_16x16x32_bf16 v[12:15], v[166:169], v[222:225], v[12:15]
	v_mfma_f32_16x16x32_bf16 v[64:67], v[162:165], v[194:197], v[64:67]
	v_mfma_f32_16x16x32_bf16 v[60:63], v[170:173], v[194:197], v[60:63]
	v_mfma_f32_16x16x32_bf16 v[48:51], v[162:165], v[210:213], v[48:51]
	v_mfma_f32_16x16x32_bf16 v[44:47], v[170:173], v[210:213], v[44:47]
	v_mfma_f32_16x16x32_bf16 v[32:35], v[162:165], v[218:221], v[32:35]
	v_mfma_f32_16x16x32_bf16 v[28:31], v[170:173], v[218:221], v[28:31]
	v_mfma_f32_16x16x32_bf16 v[16:19], v[162:165], v[226:229], v[16:19]
	v_mfma_f32_16x16x32_bf16 v[12:15], v[170:173], v[226:229], v[12:15]
	v_mfma_f32_16x16x32_bf16 v[56:59], v[174:177], v[190:193], v[56:59]
	v_mfma_f32_16x16x32_bf16 v[52:55], v[182:185], v[190:193], v[52:55]
	v_mfma_f32_16x16x32_bf16 v[40:43], v[174:177], v[198:201], v[40:43]
	v_mfma_f32_16x16x32_bf16 v[36:39], v[182:185], v[198:201], v[36:39]
	v_mfma_f32_16x16x32_bf16 v[24:27], v[174:177], v[214:217], v[24:27]
	v_mfma_f32_16x16x32_bf16 v[20:23], v[182:185], v[214:217], v[20:23]
	v_mfma_f32_16x16x32_bf16 v[6:9], v[174:177], v[222:225], v[8:11]
	v_mfma_f32_16x16x32_bf16 v[2:5], v[182:185], v[222:225], v[2:5]
	v_mfma_f32_16x16x32_bf16 v[56:59], v[178:181], v[194:197], v[56:59]
	v_mfma_f32_16x16x32_bf16 v[52:55], v[186:189], v[194:197], v[52:55]
	v_mfma_f32_16x16x32_bf16 v[40:43], v[178:181], v[210:213], v[40:43]
	v_mfma_f32_16x16x32_bf16 v[36:39], v[186:189], v[210:213], v[36:39]
	v_mfma_f32_16x16x32_bf16 v[24:27], v[178:181], v[218:221], v[24:27]
	v_mfma_f32_16x16x32_bf16 v[20:23], v[186:189], v[218:221], v[20:23]
	v_mfma_f32_16x16x32_bf16 v[8:11], v[178:181], v[226:229], v[6:9]
	v_mfma_f32_16x16x32_bf16 v[4:7], v[186:189], v[226:229], v[2:5]
	s_barrier
	s_setprio 0
	s_add_u32 s6, s6, 0x100
	s_addc_u32 s7, s7, 0
	s_add_i32 s23, s23, 2
	s_cmp_gt_u32 s23, 61
	s_cbranch_scc1 .LBB0_1547

.LBB0_1637:
	ds_read_b128 v[152:155], v149
	ds_read_b128 v[156:159], v149 offset:1024
	ds_read_b128 v[160:163], v149 offset:2048
	ds_read_b128 v[164:167], v149 offset:3072
	ds_read_b128 v[168:171], v150
	ds_read_b128 v[172:175], v150 offset:1024
	ds_read_b128 v[176:179], v150 offset:2048
	ds_read_b128 v[180:183], v150 offset:3072
	s_add_u32 s0, s42, 0xfff00080
	s_addc_u32 s1, s43, -1
	s_cmp_eq_u32 s68, 60
	s_cselect_b32 s47, s35, s1
	s_cselect_b32 s46, s64, s0
	s_cselect_b32 s45, s31, s67
	s_cselect_b32 s44, s65, s66
	s_add_i32 m0, s41, 0xc000
	ds_read_b128 v[184:187], v151
	ds_read_b128 v[188:191], v151 offset:1024
	ds_read_b128 v[192:195], v151 offset:2048
	ds_read_b128 v[196:199], v151 offset:3072
	ds_read_b128 v[200:203], v151 offset:4096
	ds_read_b128 v[210:213], v151 offset:5120
	ds_read_b128 v[214:217], v151 offset:6144
	global_load_lds_dwordx4 v136, s[42:43]
	s_add_i32 m0, s41, 0xe000
	ds_read_b128 v[218:221], v151 offset:7168
	global_load_lds_dwordx4 v138, s[42:43]
	s_waitcnt vmcnt(8) lgkmcnt(0)
	s_setprio 3
	s_barrier
	v_mfma_f32_16x16x32_bf16 v[124:127], v[152:155], v[184:187], v[124:127]
	v_mfma_f32_16x16x32_bf16 v[120:123], v[160:163], v[184:187], v[120:123]
	v_mfma_f32_16x16x32_bf16 v[116:119], v[152:155], v[192:195], v[116:119]
	v_mfma_f32_16x16x32_bf16 v[108:111], v[160:163], v[192:195], v[108:111]
	v_mfma_f32_16x16x32_bf16 v[100:103], v[152:155], v[200:203], v[100:103]
	v_mfma_f32_16x16x32_bf16 v[92:95], v[160:163], v[200:203], v[92:95]
	v_mfma_f32_16x16x32_bf16 v[84:87], v[152:155], v[214:217], v[84:87]
	v_mfma_f32_16x16x32_bf16 v[76:79], v[160:163], v[214:217], v[76:79]
	v_mfma_f32_16x16x32_bf16 v[124:127], v[156:159], v[188:191], v[124:127]
	v_mfma_f32_16x16x32_bf16 v[120:123], v[164:167], v[188:191], v[120:123]
	v_mfma_f32_16x16x32_bf16 v[116:119], v[156:159], v[196:199], v[116:119]
	v_mfma_f32_16x16x32_bf16 v[108:111], v[164:167], v[196:199], v[108:111]
	v_mfma_f32_16x16x32_bf16 v[100:103], v[156:159], v[210:213], v[100:103]
	v_mfma_f32_16x16x32_bf16 v[92:95], v[164:167], v[210:213], v[92:95]
	v_mfma_f32_16x16x32_bf16 v[84:87], v[156:159], v[218:221], v[84:87]
	v_mfma_f32_16x16x32_bf16 v[76:79], v[164:167], v[218:221], v[76:79]
	v_mfma_f32_16x16x32_bf16 v[112:115], v[168:171], v[184:187], v[112:115]
	v_mfma_f32_16x16x32_bf16 v[104:107], v[176:179], v[184:187], v[104:107]
	v_mfma_f32_16x16x32_bf16 v[96:99], v[168:171], v[192:195], v[96:99]
	v_mfma_f32_16x16x32_bf16 v[88:91], v[176:179], v[192:195], v[88:91]
	v_mfma_f32_16x16x32_bf16 v[80:83], v[168:171], v[200:203], v[80:83]
	v_mfma_f32_16x16x32_bf16 v[72:75], v[176:179], v[200:203], v[72:75]
	v_mfma_f32_16x16x32_bf16 v[68:71], v[168:171], v[214:217], v[68:71]
	v_mfma_f32_16x16x32_bf16 v[64:67], v[176:179], v[214:217], v[64:67]
	v_mfma_f32_16x16x32_bf16 v[112:115], v[172:175], v[188:191], v[112:115]
	v_mfma_f32_16x16x32_bf16 v[104:107], v[180:183], v[188:191], v[104:107]
	v_mfma_f32_16x16x32_bf16 v[96:99], v[172:175], v[196:199], v[96:99]
	v_mfma_f32_16x16x32_bf16 v[88:91], v[180:183], v[196:199], v[88:91]
	v_mfma_f32_16x16x32_bf16 v[80:83], v[172:175], v[210:213], v[80:83]
	v_mfma_f32_16x16x32_bf16 v[72:75], v[180:183], v[210:213], v[72:75]
	v_mfma_f32_16x16x32_bf16 v[68:71], v[172:175], v[218:221], v[68:71]
	v_mfma_f32_16x16x32_bf16 v[64:67], v[180:183], v[218:221], v[64:67]
	s_barrier
	s_setprio 0
	s_add_i32 s0, s57, s49
	s_mov_b32 m0, s0
	ds_read_b128 v[184:187], v151 offset:16384
	ds_read_b128 v[188:191], v151 offset:17408
	ds_read_b128 v[192:195], v151 offset:18432
	ds_read_b128 v[196:199], v151 offset:19456
	ds_read_b128 v[200:203], v151 offset:20480
	global_load_lds_dwordx4 v130, s[44:45]
	s_add_i32 m0, s0, 0x2000
	s_add_u32 s0, s44, 0x100000
	s_addc_u32 s1, s45, 0
	s_add_i32 s69, s58, s49
	global_load_lds_dwordx4 v134, s[44:45]
	s_mov_b32 m0, s69
	s_nop 0
	global_load_lds_dwordx4 v130, s[0:1]
	s_add_i32 m0, s69, 0x2000
	ds_read_b128 v[218:221], v151 offset:23552
	global_load_lds_dwordx4 v134, s[0:1]
	s_mov_b32 m0, s41
	ds_read_b128 v[214:217], v151 offset:22528
	global_load_lds_dwordx4 v128, s[46:47]
	s_mov_b32 m0, s50
	ds_read_b128 v[210:213], v151 offset:21504
	global_load_lds_dwordx4 v132, s[46:47]
	s_waitcnt vmcnt(8) lgkmcnt(0)
	s_setprio 3
	s_barrier
	v_mfma_f32_16x16x32_bf16 v[60:63], v[152:155], v[184:187], v[60:63]
	v_mfma_f32_16x16x32_bf16 v[56:59], v[160:163], v[184:187], v[56:59]
	v_mfma_f32_16x16x32_bf16 v[52:55], v[152:155], v[192:195], v[52:55]
	v_mfma_f32_16x16x32_bf16 v[44:47], v[160:163], v[192:195], v[44:47]
	v_mfma_f32_16x16x32_bf16 v[36:39], v[152:155], v[200:203], v[36:39]
	v_mfma_f32_16x16x32_bf16 v[28:31], v[160:163], v[200:203], v[28:31]
	v_mfma_f32_16x16x32_bf16 v[20:23], v[152:155], v[214:217], v[20:23]
	v_mfma_f32_16x16x32_bf16 v[12:15], v[160:163], v[214:217], v[12:15]
	v_mfma_f32_16x16x32_bf16 v[60:63], v[156:159], v[188:191], v[60:63]
	v_mfma_f32_16x16x32_bf16 v[56:59], v[164:167], v[188:191], v[56:59]
	v_mfma_f32_16x16x32_bf16 v[52:55], v[156:159], v[196:199], v[52:55]
	v_mfma_f32_16x16x32_bf16 v[44:47], v[164:167], v[196:199], v[44:47]
	v_mfma_f32_16x16x32_bf16 v[36:39], v[156:159], v[210:213], v[36:39]
	v_mfma_f32_16x16x32_bf16 v[28:31], v[164:167], v[210:213], v[28:31]
	v_mfma_f32_16x16x32_bf16 v[20:23], v[156:159], v[218:221], v[20:23]
	v_mfma_f32_16x16x32_bf16 v[12:15], v[164:167], v[218:221], v[12:15]
	v_mfma_f32_16x16x32_bf16 v[48:51], v[168:171], v[184:187], v[48:51]
	v_mfma_f32_16x16x32_bf16 v[40:43], v[176:179], v[184:187], v[40:43]
	v_mfma_f32_16x16x32_bf16 v[32:35], v[168:171], v[192:195], v[32:35]
	v_mfma_f32_16x16x32_bf16 v[24:27], v[176:179], v[192:195], v[24:27]
	v_mfma_f32_16x16x32_bf16 v[16:19], v[168:171], v[200:203], v[16:19]
	v_mfma_f32_16x16x32_bf16 v[8:11], v[176:179], v[200:203], v[8:11]
	v_mfma_f32_16x16x32_bf16 v[4:7], v[168:171], v[214:217], v[4:7]
	v_mfma_f32_16x16x32_bf16 v[0:3], v[176:179], v[214:217], v[0:3]
	v_mfma_f32_16x16x32_bf16 v[48:51], v[172:175], v[188:191], v[48:51]
	v_mfma_f32_16x16x32_bf16 v[40:43], v[180:183], v[188:191], v[40:43]
	v_mfma_f32_16x16x32_bf16 v[32:35], v[172:175], v[196:199], v[32:35]
	v_mfma_f32_16x16x32_bf16 v[24:27], v[180:183], v[196:199], v[24:27]
	v_mfma_f32_16x16x32_bf16 v[16:19], v[172:175], v[210:213], v[16:19]
	v_mfma_f32_16x16x32_bf16 v[8:11], v[180:183], v[210:213], v[8:11]
	v_mfma_f32_16x16x32_bf16 v[4:7], v[172:175], v[218:221], v[4:7]
	v_mfma_f32_16x16x32_bf16 v[0:3], v[180:183], v[218:221], v[0:3]
	s_barrier
	s_setprio 0
	s_add_i32 s69, 0, 0x18000
	s_add_i32 s70, 0, 0x1c000
	ds_read_b128 v[152:155], v228
	ds_read_b128 v[156:159], v228 offset:1024
	ds_read_b128 v[160:163], v228 offset:2048
	ds_read_b128 v[164:167], v228 offset:3072
	ds_read_b128 v[168:171], v229
	ds_read_b128 v[172:175], v229 offset:1024
	ds_read_b128 v[176:179], v229 offset:2048
	ds_read_b128 v[180:183], v229 offset:3072
	s_add_u32 s0, s46, 0x100000
	s_addc_u32 s1, s47, 0
	s_mov_b32 m0, s51
	ds_read_b128 v[184:187], v151 offset:32768
	ds_read_b128 v[188:191], v151 offset:33792
	ds_read_b128 v[192:195], v151 offset:34816
	ds_read_b128 v[196:199], v151 offset:35840
	ds_read_b128 v[200:203], v151 offset:36864
	ds_read_b128 v[210:213], v151 offset:37888
	ds_read_b128 v[214:217], v151 offset:38912
	global_load_lds_dwordx4 v128, s[0:1]
	s_mov_b32 m0, s52
	ds_read_b128 v[218:221], v151 offset:39936
	global_load_lds_dwordx4 v132, s[0:1]
	s_waitcnt vmcnt(8) lgkmcnt(0)
	s_setprio 3
	s_barrier
	v_mfma_f32_16x16x32_bf16 v[124:127], v[152:155], v[184:187], v[124:127]
	v_mfma_f32_16x16x32_bf16 v[120:123], v[160:163], v[184:187], v[120:123]
	v_mfma_f32_16x16x32_bf16 v[116:119], v[152:155], v[192:195], v[116:119]
	v_mfma_f32_16x16x32_bf16 v[108:111], v[160:163], v[192:195], v[108:111]
	v_mfma_f32_16x16x32_bf16 v[100:103], v[152:155], v[200:203], v[100:103]
	v_mfma_f32_16x16x32_bf16 v[92:95], v[160:163], v[200:203], v[92:95]
	v_mfma_f32_16x16x32_bf16 v[84:87], v[152:155], v[214:217], v[84:87]
	v_mfma_f32_16x16x32_bf16 v[76:79], v[160:163], v[214:217], v[76:79]
	v_mfma_f32_16x16x32_bf16 v[124:127], v[156:159], v[188:191], v[124:127]
	v_mfma_f32_16x16x32_bf16 v[120:123], v[164:167], v[188:191], v[120:123]
	v_mfma_f32_16x16x32_bf16 v[116:119], v[156:159], v[196:199], v[116:119]
	v_mfma_f32_16x16x32_bf16 v[108:111], v[164:167], v[196:199], v[108:111]
	v_mfma_f32_16x16x32_bf16 v[100:103], v[156:159], v[210:213], v[100:103]
	v_mfma_f32_16x16x32_bf16 v[92:95], v[164:167], v[210:213], v[92:95]
	v_mfma_f32_16x16x32_bf16 v[84:87], v[156:159], v[218:221], v[84:87]
	v_mfma_f32_16x16x32_bf16 v[76:79], v[164:167], v[218:221], v[76:79]
	v_mfma_f32_16x16x32_bf16 v[112:115], v[168:171], v[184:187], v[112:115]
	v_mfma_f32_16x16x32_bf16 v[104:107], v[176:179], v[184:187], v[104:107]
	v_mfma_f32_16x16x32_bf16 v[96:99], v[168:171], v[192:195], v[96:99]
	v_mfma_f32_16x16x32_bf16 v[88:91], v[176:179], v[192:195], v[88:91]
	v_mfma_f32_16x16x32_bf16 v[80:83], v[168:171], v[200:203], v[80:83]
	v_mfma_f32_16x16x32_bf16 v[72:75], v[176:179], v[200:203], v[72:75]
	v_mfma_f32_16x16x32_bf16 v[68:71], v[168:171], v[214:217], v[68:71]
	v_mfma_f32_16x16x32_bf16 v[64:67], v[176:179], v[214:217], v[64:67]
	v_mfma_f32_16x16x32_bf16 v[112:115], v[172:175], v[188:191], v[112:115]
	v_mfma_f32_16x16x32_bf16 v[104:107], v[180:183], v[188:191], v[104:107]
	v_mfma_f32_16x16x32_bf16 v[96:99], v[172:175], v[196:199], v[96:99]
	v_mfma_f32_16x16x32_bf16 v[88:91], v[180:183], v[196:199], v[88:91]
	v_mfma_f32_16x16x32_bf16 v[80:83], v[172:175], v[210:213], v[80:83]
	v_mfma_f32_16x16x32_bf16 v[72:75], v[180:183], v[210:213], v[72:75]
	v_mfma_f32_16x16x32_bf16 v[68:71], v[172:175], v[218:221], v[68:71]
	v_mfma_f32_16x16x32_bf16 v[64:67], v[180:183], v[218:221], v[64:67]
	s_barrier
	s_setprio 0
	s_add_i32 s0, s69, s49
	s_add_u32 s100, s44, 0x80
	s_addc_u32 s101, s45, 0
	s_mov_b32 m0, s0
	ds_read_b128 v[184:187], v151 offset:49152
	ds_read_b128 v[188:191], v151 offset:50176
	ds_read_b128 v[192:195], v151 offset:51200
	ds_read_b128 v[196:199], v151 offset:52224
	global_load_lds_dwordx4 v130, s[100:101]
	s_add_i32 m0, s0, 0x2000
	s_add_u32 s0, s44, 0x100080
	s_addc_u32 s1, s45, 0
	s_add_i32 s44, s70, s49
	global_load_lds_dwordx4 v134, s[100:101]
	s_mov_b32 m0, s44
	ds_read_b128 v[218:221], v151 offset:56320
	global_load_lds_dwordx4 v130, s[0:1]
	s_add_i32 m0, s44, 0x2000
	ds_read_b128 v[214:217], v151 offset:55296
	global_load_lds_dwordx4 v134, s[0:1]
	s_add_u32 s100, s46, 0x80
	s_addc_u32 s101, s47, 0
	s_mov_b32 m0, s54
	ds_read_b128 v[210:213], v151 offset:54272
	global_load_lds_dwordx4 v128, s[100:101]
	s_mov_b32 m0, s55
	ds_read_b128 v[200:203], v151 offset:53248
	global_load_lds_dwordx4 v132, s[100:101]
	s_waitcnt vmcnt(8) lgkmcnt(0)
	s_setprio 3
	s_barrier
	v_mfma_f32_16x16x32_bf16 v[60:63], v[152:155], v[184:187], v[60:63]
	v_mfma_f32_16x16x32_bf16 v[56:59], v[160:163], v[184:187], v[56:59]
	v_mfma_f32_16x16x32_bf16 v[52:55], v[152:155], v[192:195], v[52:55]
	v_mfma_f32_16x16x32_bf16 v[44:47], v[160:163], v[192:195], v[44:47]
	v_mfma_f32_16x16x32_bf16 v[36:39], v[152:155], v[200:203], v[36:39]
	v_mfma_f32_16x16x32_bf16 v[28:31], v[160:163], v[200:203], v[28:31]
	v_mfma_f32_16x16x32_bf16 v[20:23], v[152:155], v[214:217], v[20:23]
	v_mfma_f32_16x16x32_bf16 v[12:15], v[160:163], v[214:217], v[12:15]
	v_mfma_f32_16x16x32_bf16 v[60:63], v[156:159], v[188:191], v[60:63]
	v_mfma_f32_16x16x32_bf16 v[56:59], v[164:167], v[188:191], v[56:59]
	v_mfma_f32_16x16x32_bf16 v[52:55], v[156:159], v[196:199], v[52:55]
	v_mfma_f32_16x16x32_bf16 v[44:47], v[164:167], v[196:199], v[44:47]
	v_mfma_f32_16x16x32_bf16 v[36:39], v[156:159], v[210:213], v[36:39]
	v_mfma_f32_16x16x32_bf16 v[28:31], v[164:167], v[210:213], v[28:31]
	v_mfma_f32_16x16x32_bf16 v[20:23], v[156:159], v[218:221], v[20:23]
	v_mfma_f32_16x16x32_bf16 v[12:15], v[164:167], v[218:221], v[12:15]
	v_mfma_f32_16x16x32_bf16 v[48:51], v[168:171], v[184:187], v[48:51]
	v_mfma_f32_16x16x32_bf16 v[40:43], v[176:179], v[184:187], v[40:43]
	v_mfma_f32_16x16x32_bf16 v[32:35], v[168:171], v[192:195], v[32:35]
	v_mfma_f32_16x16x32_bf16 v[24:27], v[176:179], v[192:195], v[24:27]
	v_mfma_f32_16x16x32_bf16 v[16:19], v[168:171], v[200:203], v[16:19]
	v_mfma_f32_16x16x32_bf16 v[8:11], v[176:179], v[200:203], v[8:11]
	v_mfma_f32_16x16x32_bf16 v[4:7], v[168:171], v[214:217], v[4:7]
	v_mfma_f32_16x16x32_bf16 v[0:3], v[176:179], v[214:217], v[0:3]
	v_mfma_f32_16x16x32_bf16 v[48:51], v[172:175], v[188:191], v[48:51]
	v_mfma_f32_16x16x32_bf16 v[40:43], v[180:183], v[188:191], v[40:43]
	v_mfma_f32_16x16x32_bf16 v[32:35], v[172:175], v[196:199], v[32:35]
	v_mfma_f32_16x16x32_bf16 v[24:27], v[180:183], v[196:199], v[24:27]
	v_mfma_f32_16x16x32_bf16 v[16:19], v[172:175], v[210:213], v[16:19]
	v_mfma_f32_16x16x32_bf16 v[8:11], v[180:183], v[210:213], v[8:11]
	v_mfma_f32_16x16x32_bf16 v[4:7], v[172:175], v[218:221], v[4:7]
	v_mfma_f32_16x16x32_bf16 v[0:3], v[180:183], v[218:221], v[0:3]
	s_barrier
	s_setprio 0
	s_add_u32 s42, s42, 0x100
	s_addc_u32 s43, s43, 0
	s_add_i32 s68, s68, 2
	s_add_u32 s66, s66, 0x100
	s_addc_u32 s67, s67, 0
	s_cmp_gt_u32 s68, 61
	s_cbranch_scc0 .LBB0_1637
	s_and_b64 vcc, exec, s[16:17]
	s_cbranch_vccz .LBB0_1640
	s_barrier

.LBB0_1813:
	ds_read_b128 v[148:151], v156
	ds_read_b128 v[160:163], v156 offset:1024
	ds_read_b128 v[164:167], v156 offset:2048
	ds_read_b128 v[168:171], v156 offset:3072
	ds_read_b128 v[172:175], v157
	ds_read_b128 v[176:179], v157 offset:1024
	ds_read_b128 v[180:183], v157 offset:2048
	ds_read_b128 v[184:187], v157 offset:3072
	s_add_u32 s0, s36, 0xfff00080
	s_addc_u32 s1, s37, -1
	s_cmp_eq_u32 s64, 60
	s_cselect_b32 s41, s59, s1
	s_cselect_b32 s40, s60, s0
	s_cselect_b32 s39, s17, s63
	s_cselect_b32 s38, s61, s62
	s_add_i32 m0, s31, 0xc000
	ds_read_b128 v[188:191], v158
	ds_read_b128 v[192:195], v158 offset:1024
	ds_read_b128 v[196:199], v158 offset:2048
	ds_read_b128 v[200:203], v158 offset:3072
	ds_read_b128 v[210:213], v158 offset:4096
	ds_read_b128 v[214:217], v158 offset:5120
	ds_read_b128 v[218:221], v158 offset:6144
	global_load_lds_dwordx4 v140, s[36:37]
	s_add_i32 m0, s31, 0xe000
	ds_read_b128 v[222:225], v158 offset:7168
	global_load_lds_dwordx4 v142, s[36:37]
	s_waitcnt vmcnt(8) lgkmcnt(0)
	s_setprio 3
	s_barrier
	v_mfma_f32_16x16x32_bf16 v[124:127], v[148:151], v[188:191], v[124:127]
	v_mfma_f32_16x16x32_bf16 v[120:123], v[164:167], v[188:191], v[120:123]
	v_mfma_f32_16x16x32_bf16 v[108:111], v[148:151], v[196:199], v[108:111]
	v_mfma_f32_16x16x32_bf16 v[104:107], v[164:167], v[196:199], v[104:107]
	v_mfma_f32_16x16x32_bf16 v[92:95], v[148:151], v[210:213], v[92:95]
	v_mfma_f32_16x16x32_bf16 v[88:91], v[164:167], v[210:213], v[88:91]
	v_mfma_f32_16x16x32_bf16 v[76:79], v[148:151], v[218:221], v[76:79]
	v_mfma_f32_16x16x32_bf16 v[72:75], v[164:167], v[218:221], v[72:75]
	v_mfma_f32_16x16x32_bf16 v[124:127], v[160:163], v[192:195], v[124:127]
	v_mfma_f32_16x16x32_bf16 v[120:123], v[168:171], v[192:195], v[120:123]
	v_mfma_f32_16x16x32_bf16 v[108:111], v[160:163], v[200:203], v[108:111]
	v_mfma_f32_16x16x32_bf16 v[104:107], v[168:171], v[200:203], v[104:107]
	v_mfma_f32_16x16x32_bf16 v[92:95], v[160:163], v[214:217], v[92:95]
	v_mfma_f32_16x16x32_bf16 v[88:91], v[168:171], v[214:217], v[88:91]
	v_mfma_f32_16x16x32_bf16 v[76:79], v[160:163], v[222:225], v[76:79]
	v_mfma_f32_16x16x32_bf16 v[72:75], v[168:171], v[222:225], v[72:75]
	v_mfma_f32_16x16x32_bf16 v[116:119], v[172:175], v[188:191], v[116:119]
	v_mfma_f32_16x16x32_bf16 v[112:115], v[180:183], v[188:191], v[112:115]
	v_mfma_f32_16x16x32_bf16 v[100:103], v[172:175], v[196:199], v[100:103]
	v_mfma_f32_16x16x32_bf16 v[96:99], v[180:183], v[196:199], v[96:99]
	v_mfma_f32_16x16x32_bf16 v[84:87], v[172:175], v[210:213], v[84:87]
	v_mfma_f32_16x16x32_bf16 v[80:83], v[180:183], v[210:213], v[80:83]
	v_mfma_f32_16x16x32_bf16 v[68:71], v[172:175], v[218:221], v[68:71]
	v_mfma_f32_16x16x32_bf16 v[64:67], v[180:183], v[218:221], v[64:67]
	v_mfma_f32_16x16x32_bf16 v[116:119], v[176:179], v[192:195], v[116:119]
	v_mfma_f32_16x16x32_bf16 v[112:115], v[184:187], v[192:195], v[112:115]
	v_mfma_f32_16x16x32_bf16 v[100:103], v[176:179], v[200:203], v[100:103]
	v_mfma_f32_16x16x32_bf16 v[96:99], v[184:187], v[200:203], v[96:99]
	v_mfma_f32_16x16x32_bf16 v[84:87], v[176:179], v[214:217], v[84:87]
	v_mfma_f32_16x16x32_bf16 v[80:83], v[184:187], v[214:217], v[80:83]
	v_mfma_f32_16x16x32_bf16 v[68:71], v[176:179], v[222:225], v[68:71]
	v_mfma_f32_16x16x32_bf16 v[64:67], v[184:187], v[222:225], v[64:67]
	s_barrier
	s_setprio 0
	s_add_i32 s0, s52, s43
	s_mov_b32 m0, s0
	ds_read_b128 v[188:191], v158 offset:16384
	ds_read_b128 v[192:195], v158 offset:17408
	ds_read_b128 v[196:199], v158 offset:18432
	ds_read_b128 v[200:203], v158 offset:19456
	ds_read_b128 v[210:213], v158 offset:20480
	global_load_lds_dwordx4 v132, s[38:39]
	s_add_i32 m0, s0, 0x2000
	s_add_u32 s0, s38, 0x100000
	s_addc_u32 s1, s39, 0
	s_add_i32 s65, s53, s43
	global_load_lds_dwordx4 v136, s[38:39]
	s_mov_b32 m0, s65
	s_nop 0
	global_load_lds_dwordx4 v132, s[0:1]
	s_add_i32 m0, s65, 0x2000
	ds_read_b128 v[222:225], v158 offset:23552
	global_load_lds_dwordx4 v136, s[0:1]
	s_mov_b32 m0, s31
	ds_read_b128 v[218:221], v158 offset:22528
	global_load_lds_dwordx4 v130, s[40:41]
	s_mov_b32 m0, s35
	ds_read_b128 v[214:217], v158 offset:21504
	global_load_lds_dwordx4 v134, s[40:41]
	s_waitcnt vmcnt(8) lgkmcnt(0)
	s_setprio 3
	s_barrier
	v_mfma_f32_16x16x32_bf16 v[60:63], v[148:151], v[188:191], v[60:63]
	v_mfma_f32_16x16x32_bf16 v[56:59], v[164:167], v[188:191], v[56:59]
	v_mfma_f32_16x16x32_bf16 v[44:47], v[148:151], v[196:199], v[44:47]
	v_mfma_f32_16x16x32_bf16 v[40:43], v[164:167], v[196:199], v[40:43]
	v_mfma_f32_16x16x32_bf16 v[28:31], v[148:151], v[210:213], v[28:31]
	v_mfma_f32_16x16x32_bf16 v[24:27], v[164:167], v[210:213], v[24:27]
	v_mfma_f32_16x16x32_bf16 v[12:15], v[148:151], v[218:221], v[12:15]
	v_mfma_f32_16x16x32_bf16 v[8:11], v[164:167], v[218:221], v[8:11]
	v_mfma_f32_16x16x32_bf16 v[60:63], v[160:163], v[192:195], v[60:63]
	v_mfma_f32_16x16x32_bf16 v[56:59], v[168:171], v[192:195], v[56:59]
	v_mfma_f32_16x16x32_bf16 v[44:47], v[160:163], v[200:203], v[44:47]
	v_mfma_f32_16x16x32_bf16 v[40:43], v[168:171], v[200:203], v[40:43]
	v_mfma_f32_16x16x32_bf16 v[28:31], v[160:163], v[214:217], v[28:31]
	v_mfma_f32_16x16x32_bf16 v[24:27], v[168:171], v[214:217], v[24:27]
	v_mfma_f32_16x16x32_bf16 v[12:15], v[160:163], v[222:225], v[12:15]
	v_mfma_f32_16x16x32_bf16 v[8:11], v[168:171], v[222:225], v[8:11]
	v_mfma_f32_16x16x32_bf16 v[52:55], v[172:175], v[188:191], v[52:55]
	v_mfma_f32_16x16x32_bf16 v[48:51], v[180:183], v[188:191], v[48:51]
	v_mfma_f32_16x16x32_bf16 v[36:39], v[172:175], v[196:199], v[36:39]
	v_mfma_f32_16x16x32_bf16 v[32:35], v[180:183], v[196:199], v[32:35]
	v_mfma_f32_16x16x32_bf16 v[20:23], v[172:175], v[210:213], v[20:23]
	v_mfma_f32_16x16x32_bf16 v[16:19], v[180:183], v[210:213], v[16:19]
	v_mfma_f32_16x16x32_bf16 v[4:7], v[172:175], v[218:221], v[4:7]
	v_mfma_f32_16x16x32_bf16 v[0:3], v[180:183], v[218:221], v[0:3]
	v_mfma_f32_16x16x32_bf16 v[52:55], v[176:179], v[192:195], v[52:55]
	v_mfma_f32_16x16x32_bf16 v[48:51], v[184:187], v[192:195], v[48:51]
	v_mfma_f32_16x16x32_bf16 v[36:39], v[176:179], v[200:203], v[36:39]
	v_mfma_f32_16x16x32_bf16 v[32:35], v[184:187], v[200:203], v[32:35]
	v_mfma_f32_16x16x32_bf16 v[20:23], v[176:179], v[214:217], v[20:23]
	v_mfma_f32_16x16x32_bf16 v[16:19], v[184:187], v[214:217], v[16:19]
	v_mfma_f32_16x16x32_bf16 v[4:7], v[176:179], v[222:225], v[4:7]
	v_mfma_f32_16x16x32_bf16 v[0:3], v[184:187], v[222:225], v[0:3]
	s_barrier
	s_setprio 0
	s_add_i32 s65, 0, 0x18000
	s_add_i32 s66, 0, 0x1c000
	ds_read_b128 v[148:151], v234
	ds_read_b128 v[160:163], v234 offset:1024
	ds_read_b128 v[164:167], v234 offset:2048
	ds_read_b128 v[168:171], v234 offset:3072
	ds_read_b128 v[172:175], v235
	ds_read_b128 v[176:179], v235 offset:1024
	ds_read_b128 v[180:183], v235 offset:2048
	ds_read_b128 v[184:187], v235 offset:3072
	s_add_u32 s0, s40, 0x100000
	s_addc_u32 s1, s41, 0
	s_mov_b32 m0, s44
	ds_read_b128 v[188:191], v158 offset:32768
	ds_read_b128 v[192:195], v158 offset:33792
	ds_read_b128 v[196:199], v158 offset:34816
	ds_read_b128 v[200:203], v158 offset:35840
	ds_read_b128 v[210:213], v158 offset:36864
	ds_read_b128 v[214:217], v158 offset:37888
	ds_read_b128 v[218:221], v158 offset:38912
	global_load_lds_dwordx4 v130, s[0:1]
	s_mov_b32 m0, s45
	ds_read_b128 v[222:225], v158 offset:39936
	global_load_lds_dwordx4 v134, s[0:1]
	s_waitcnt vmcnt(8) lgkmcnt(0)
	s_setprio 3
	s_barrier
	v_mfma_f32_16x16x32_bf16 v[124:127], v[148:151], v[188:191], v[124:127]
	v_mfma_f32_16x16x32_bf16 v[120:123], v[164:167], v[188:191], v[120:123]
	v_mfma_f32_16x16x32_bf16 v[108:111], v[148:151], v[196:199], v[108:111]
	v_mfma_f32_16x16x32_bf16 v[104:107], v[164:167], v[196:199], v[104:107]
	v_mfma_f32_16x16x32_bf16 v[92:95], v[148:151], v[210:213], v[92:95]
	v_mfma_f32_16x16x32_bf16 v[88:91], v[164:167], v[210:213], v[88:91]
	v_mfma_f32_16x16x32_bf16 v[76:79], v[148:151], v[218:221], v[76:79]
	v_mfma_f32_16x16x32_bf16 v[72:75], v[164:167], v[218:221], v[72:75]
	v_mfma_f32_16x16x32_bf16 v[124:127], v[160:163], v[192:195], v[124:127]
	v_mfma_f32_16x16x32_bf16 v[120:123], v[168:171], v[192:195], v[120:123]
	v_mfma_f32_16x16x32_bf16 v[108:111], v[160:163], v[200:203], v[108:111]
	v_mfma_f32_16x16x32_bf16 v[104:107], v[168:171], v[200:203], v[104:107]
	v_mfma_f32_16x16x32_bf16 v[92:95], v[160:163], v[214:217], v[92:95]
	v_mfma_f32_16x16x32_bf16 v[88:91], v[168:171], v[214:217], v[88:91]
	v_mfma_f32_16x16x32_bf16 v[76:79], v[160:163], v[222:225], v[76:79]
	v_mfma_f32_16x16x32_bf16 v[72:75], v[168:171], v[222:225], v[72:75]
	v_mfma_f32_16x16x32_bf16 v[116:119], v[172:175], v[188:191], v[116:119]
	v_mfma_f32_16x16x32_bf16 v[112:115], v[180:183], v[188:191], v[112:115]
	v_mfma_f32_16x16x32_bf16 v[100:103], v[172:175], v[196:199], v[100:103]
	v_mfma_f32_16x16x32_bf16 v[96:99], v[180:183], v[196:199], v[96:99]
	v_mfma_f32_16x16x32_bf16 v[84:87], v[172:175], v[210:213], v[84:87]
	v_mfma_f32_16x16x32_bf16 v[80:83], v[180:183], v[210:213], v[80:83]
	v_mfma_f32_16x16x32_bf16 v[68:71], v[172:175], v[218:221], v[68:71]
	v_mfma_f32_16x16x32_bf16 v[64:67], v[180:183], v[218:221], v[64:67]
	v_mfma_f32_16x16x32_bf16 v[116:119], v[176:179], v[192:195], v[116:119]
	v_mfma_f32_16x16x32_bf16 v[112:115], v[184:187], v[192:195], v[112:115]
	v_mfma_f32_16x16x32_bf16 v[100:103], v[176:179], v[200:203], v[100:103]
	v_mfma_f32_16x16x32_bf16 v[96:99], v[184:187], v[200:203], v[96:99]
	v_mfma_f32_16x16x32_bf16 v[84:87], v[176:179], v[214:217], v[84:87]
	v_mfma_f32_16x16x32_bf16 v[80:83], v[184:187], v[214:217], v[80:83]
	v_mfma_f32_16x16x32_bf16 v[68:71], v[176:179], v[222:225], v[68:71]
	v_mfma_f32_16x16x32_bf16 v[64:67], v[184:187], v[222:225], v[64:67]
	s_barrier
	s_setprio 0
	s_add_i32 s0, s65, s43
	s_add_u32 s100, s38, 0x80
	s_addc_u32 s101, s39, 0
	s_mov_b32 m0, s0
	ds_read_b128 v[188:191], v158 offset:49152
	ds_read_b128 v[192:195], v158 offset:50176
	ds_read_b128 v[196:199], v158 offset:51200
	ds_read_b128 v[200:203], v158 offset:52224
	global_load_lds_dwordx4 v132, s[100:101]
	s_add_i32 m0, s0, 0x2000
	s_add_u32 s0, s38, 0x100080
	s_addc_u32 s1, s39, 0
	s_add_i32 s38, s66, s43
	global_load_lds_dwordx4 v136, s[100:101]
	s_mov_b32 m0, s38
	ds_read_b128 v[222:225], v158 offset:56320
	global_load_lds_dwordx4 v132, s[0:1]
	s_add_i32 m0, s38, 0x2000
	ds_read_b128 v[218:221], v158 offset:55296
	global_load_lds_dwordx4 v136, s[0:1]
	s_add_u32 s100, s40, 0x80
	s_addc_u32 s101, s41, 0
	s_mov_b32 m0, s49
	ds_read_b128 v[214:217], v158 offset:54272
	global_load_lds_dwordx4 v130, s[100:101]
	s_mov_b32 m0, s50
	ds_read_b128 v[210:213], v158 offset:53248
	global_load_lds_dwordx4 v134, s[100:101]
	s_waitcnt vmcnt(8) lgkmcnt(0)
	s_setprio 3
	s_barrier
	v_mfma_f32_16x16x32_bf16 v[60:63], v[148:151], v[188:191], v[60:63]
	v_mfma_f32_16x16x32_bf16 v[56:59], v[164:167], v[188:191], v[56:59]
	v_mfma_f32_16x16x32_bf16 v[44:47], v[148:151], v[196:199], v[44:47]
	v_mfma_f32_16x16x32_bf16 v[40:43], v[164:167], v[196:199], v[40:43]
	v_mfma_f32_16x16x32_bf16 v[28:31], v[148:151], v[210:213], v[28:31]
	v_mfma_f32_16x16x32_bf16 v[24:27], v[164:167], v[210:213], v[24:27]
	v_mfma_f32_16x16x32_bf16 v[12:15], v[148:151], v[218:221], v[12:15]
	v_mfma_f32_16x16x32_bf16 v[8:11], v[164:167], v[218:221], v[8:11]
	v_mfma_f32_16x16x32_bf16 v[60:63], v[160:163], v[192:195], v[60:63]
	v_mfma_f32_16x16x32_bf16 v[56:59], v[168:171], v[192:195], v[56:59]
	v_mfma_f32_16x16x32_bf16 v[44:47], v[160:163], v[200:203], v[44:47]
	v_mfma_f32_16x16x32_bf16 v[40:43], v[168:171], v[200:203], v[40:43]
	v_mfma_f32_16x16x32_bf16 v[28:31], v[160:163], v[214:217], v[28:31]
	v_mfma_f32_16x16x32_bf16 v[24:27], v[168:171], v[214:217], v[24:27]
	v_mfma_f32_16x16x32_bf16 v[12:15], v[160:163], v[222:225], v[12:15]
	v_mfma_f32_16x16x32_bf16 v[8:11], v[168:171], v[222:225], v[8:11]
	v_mfma_f32_16x16x32_bf16 v[52:55], v[172:175], v[188:191], v[52:55]
	v_mfma_f32_16x16x32_bf16 v[48:51], v[180:183], v[188:191], v[48:51]
	v_mfma_f32_16x16x32_bf16 v[36:39], v[172:175], v[196:199], v[36:39]
	v_mfma_f32_16x16x32_bf16 v[32:35], v[180:183], v[196:199], v[32:35]
	v_mfma_f32_16x16x32_bf16 v[20:23], v[172:175], v[210:213], v[20:23]
	v_mfma_f32_16x16x32_bf16 v[16:19], v[180:183], v[210:213], v[16:19]
	v_mfma_f32_16x16x32_bf16 v[4:7], v[172:175], v[218:221], v[4:7]
	v_mfma_f32_16x16x32_bf16 v[0:3], v[180:183], v[218:221], v[0:3]
	v_mfma_f32_16x16x32_bf16 v[52:55], v[176:179], v[192:195], v[52:55]
	v_mfma_f32_16x16x32_bf16 v[48:51], v[184:187], v[192:195], v[48:51]
	v_mfma_f32_16x16x32_bf16 v[36:39], v[176:179], v[200:203], v[36:39]
	v_mfma_f32_16x16x32_bf16 v[32:35], v[184:187], v[200:203], v[32:35]
	v_mfma_f32_16x16x32_bf16 v[20:23], v[176:179], v[214:217], v[20:23]
	v_mfma_f32_16x16x32_bf16 v[16:19], v[184:187], v[214:217], v[16:19]
	v_mfma_f32_16x16x32_bf16 v[4:7], v[176:179], v[222:225], v[4:7]
	v_mfma_f32_16x16x32_bf16 v[0:3], v[184:187], v[222:225], v[0:3]
	s_barrier
	s_setprio 0
	s_add_u32 s36, s36, 0x100
	s_addc_u32 s37, s37, 0
	s_add_i32 s64, s64, 2
	s_add_u32 s62, s62, 0x100
	s_addc_u32 s63, s63, 0
	s_cmp_gt_u32 s64, 61
	s_cbranch_scc0 .LBB0_1813
	s_and_b64 vcc, exec, s[14:15]
	s_cbranch_vccz .LBB0_1816
	s_barrier

.LBB0_1833:
	ds_read_b128 v[24:27], v193
	ds_read_b128 v[28:31], v193 offset:1024
	ds_read_b128 v[16:19], v193 offset:2048
	ds_read_b128 v[20:23], v193 offset:3072
	ds_read_b128 v[8:11], v194
	ds_read_b128 v[12:15], v194 offset:1024
	ds_read_b128 v[0:3], v194 offset:2048
	ds_read_b128 v[4:7], v194 offset:3072
	s_add_u32 s0, s36, 0xfff80080
	s_addc_u32 s1, s37, -1
	s_cmp_eq_u32 s65, 28
	s_cselect_b32 s41, s26, s1
	s_cselect_b32 s40, s27, s0
	s_cselect_b32 s39, s17, s64
	s_cselect_b32 s38, s31, s63
	s_add_i32 m0, s35, 0xc000
	ds_read_b128 v[180:183], v195
	ds_read_b128 v[184:187], v195 offset:1024
	ds_read_b128 v[210:213], v195 offset:2048
	ds_read_b128 v[214:217], v195 offset:3072
	ds_read_b128 v[218:221], v195 offset:4096
	ds_read_b128 v[222:225], v195 offset:5120
	ds_read_b128 v[226:229], v195 offset:6144
	global_load_lds_dwordx4 v172, s[36:37]
	s_add_i32 m0, s35, 0xe000
	ds_read_b128 v[230:233], v195 offset:7168
	global_load_lds_dwordx4 v174, s[36:37]
	s_waitcnt vmcnt(8) lgkmcnt(0)
	s_setprio 3
	s_barrier
	v_mfma_scale_f32_16x16x128_f8f6f4 v[152:155], v[24:31], v[180:187], v[152:155], v188, v188 op_sel_hi:[0,0,0]
	v_mfma_scale_f32_16x16x128_f8f6f4 v[148:151], v[16:23], v[180:187], v[148:151], v188, v188 op_sel_hi:[0,0,0]
	v_mfma_scale_f32_16x16x128_f8f6f4 v[140:143], v[24:31], v[210:217], v[140:143], v188, v188 op_sel_hi:[0,0,0]
	v_mfma_scale_f32_16x16x128_f8f6f4 v[132:135], v[16:23], v[210:217], v[132:135], v188, v188 op_sel_hi:[0,0,0]
	v_mfma_scale_f32_16x16x128_f8f6f4 v[124:127], v[24:31], v[218:225], v[124:127], v188, v188 op_sel_hi:[0,0,0]
	v_mfma_scale_f32_16x16x128_f8f6f4 v[120:123], v[16:23], v[218:225], v[120:123], v188, v188 op_sel_hi:[0,0,0]
	v_mfma_scale_f32_16x16x128_f8f6f4 v[108:111], v[24:31], v[226:233], v[108:111], v188, v188 op_sel_hi:[0,0,0]
	v_mfma_scale_f32_16x16x128_f8f6f4 v[100:103], v[16:23], v[226:233], v[100:103], v188, v188 op_sel_hi:[0,0,0]
	v_mfma_scale_f32_16x16x128_f8f6f4 v[156:159], v[8:15], v[180:187], v[156:159], v188, v188 op_sel_hi:[0,0,0]
	v_mfma_scale_f32_16x16x128_f8f6f4 v[144:147], v[0:7], v[180:187], v[144:147], v188, v188 op_sel_hi:[0,0,0]
	v_mfma_scale_f32_16x16x128_f8f6f4 v[136:139], v[8:15], v[210:217], v[136:139], v188, v188 op_sel_hi:[0,0,0]
	v_mfma_scale_f32_16x16x128_f8f6f4 v[128:131], v[0:7], v[210:217], v[128:131], v188, v188 op_sel_hi:[0,0,0]
	v_mfma_scale_f32_16x16x128_f8f6f4 v[116:119], v[8:15], v[218:225], v[116:119], v188, v188 op_sel_hi:[0,0,0]
	v_mfma_scale_f32_16x16x128_f8f6f4 v[112:115], v[0:7], v[218:225], v[112:115], v188, v188 op_sel_hi:[0,0,0]
	v_mfma_scale_f32_16x16x128_f8f6f4 v[104:107], v[8:15], v[226:233], v[104:107], v188, v188 op_sel_hi:[0,0,0]
	v_mfma_scale_f32_16x16x128_f8f6f4 v[96:99], v[0:7], v[226:233], v[96:99], v188, v188 op_sel_hi:[0,0,0]
	s_barrier
	s_setprio 0
	s_add_i32 s0, s56, s45
	s_mov_b32 m0, s0
	ds_read_b128 v[210:213], v195 offset:16384
	ds_read_b128 v[214:217], v195 offset:17408
	ds_read_b128 v[218:221], v195 offset:18432
	ds_read_b128 v[222:225], v195 offset:19456
	ds_read_b128 v[226:229], v195 offset:20480
	global_load_lds_dwordx4 v164, s[38:39]
	s_add_i32 m0, s0, 0x2000
	s_add_u32 s0, s38, 0x80000
	s_addc_u32 s1, s39, 0
	s_add_i32 s66, s57, s45
	global_load_lds_dwordx4 v168, s[38:39]
	s_mov_b32 m0, s66
	s_nop 0
	global_load_lds_dwordx4 v164, s[0:1]
	s_add_i32 m0, s66, 0x2000
	ds_read_b128 v[238:241], v195 offset:23552
	global_load_lds_dwordx4 v168, s[0:1]
	s_mov_b32 m0, s35
	ds_read_b128 v[234:237], v195 offset:22528
	global_load_lds_dwordx4 v162, s[40:41]
	s_mov_b32 m0, s46
	ds_read_b128 v[230:233], v195 offset:21504
	global_load_lds_dwordx4 v166, s[40:41]
	s_waitcnt vmcnt(8) lgkmcnt(0)
	s_setprio 3
	s_barrier
	v_mfma_scale_f32_16x16x128_f8f6f4 v[92:95], v[24:31], v[210:217], v[92:95], v188, v188 op_sel_hi:[0,0,0]
	v_mfma_scale_f32_16x16x128_f8f6f4 v[88:91], v[16:23], v[210:217], v[88:91], v188, v188 op_sel_hi:[0,0,0]
	v_mfma_scale_f32_16x16x128_f8f6f4 v[76:79], v[24:31], v[218:225], v[76:79], v188, v188 op_sel_hi:[0,0,0]
	v_mfma_scale_f32_16x16x128_f8f6f4 v[68:71], v[16:23], v[218:225], v[68:71], v188, v188 op_sel_hi:[0,0,0]
	v_mfma_scale_f32_16x16x128_f8f6f4 v[60:63], v[24:31], v[226:233], v[60:63], v188, v188 op_sel_hi:[0,0,0]
	v_mfma_scale_f32_16x16x128_f8f6f4 v[56:59], v[16:23], v[226:233], v[56:59], v188, v188 op_sel_hi:[0,0,0]
	v_mfma_scale_f32_16x16x128_f8f6f4 v[44:47], v[24:31], v[234:241], v[44:47], v188, v188 op_sel_hi:[0,0,0]
	v_mfma_scale_f32_16x16x128_f8f6f4 v[40:43], v[16:23], v[234:241], v[40:43], v188, v188 op_sel_hi:[0,0,0]
	v_mfma_scale_f32_16x16x128_f8f6f4 v[84:87], v[8:15], v[210:217], v[84:87], v188, v188 op_sel_hi:[0,0,0]
	v_mfma_scale_f32_16x16x128_f8f6f4 v[80:83], v[0:7], v[210:217], v[80:83], v188, v188 op_sel_hi:[0,0,0]
	v_mfma_scale_f32_16x16x128_f8f6f4 v[72:75], v[8:15], v[218:225], v[72:75], v188, v188 op_sel_hi:[0,0,0]
	v_mfma_scale_f32_16x16x128_f8f6f4 v[64:67], v[0:7], v[218:225], v[64:67], v188, v188 op_sel_hi:[0,0,0]
	v_mfma_scale_f32_16x16x128_f8f6f4 v[52:55], v[8:15], v[226:233], v[52:55], v188, v188 op_sel_hi:[0,0,0]
	v_mfma_scale_f32_16x16x128_f8f6f4 v[48:51], v[0:7], v[226:233], v[48:51], v188, v188 op_sel_hi:[0,0,0]
	v_mfma_scale_f32_16x16x128_f8f6f4 v[36:39], v[8:15], v[234:241], v[36:39], v188, v188 op_sel_hi:[0,0,0]
	v_mfma_scale_f32_16x16x128_f8f6f4 v[32:35], v[0:7], v[234:241], v[32:35], v188, v188 op_sel_hi:[0,0,0]
	s_barrier
	s_setprio 0
	s_add_i32 s66, 0, 0x18000
	s_add_i32 s67, 0, 0x1c000
	ds_read_b128 v[0:3], v198
	ds_read_b128 v[4:7], v198 offset:1024
	ds_read_b128 v[8:11], v198 offset:2048
	ds_read_b128 v[12:15], v198 offset:3072
	ds_read_b128 v[16:19], v199
	ds_read_b128 v[20:23], v199 offset:1024
	ds_read_b128 v[24:27], v199 offset:2048
	ds_read_b128 v[28:31], v199 offset:3072
	s_add_u32 s0, s40, 0x80000
	s_addc_u32 s1, s41, 0
	s_mov_b32 m0, s47
	ds_read_b128 v[210:213], v195 offset:32768
	ds_read_b128 v[214:217], v195 offset:33792
	ds_read_b128 v[218:221], v195 offset:34816
	ds_read_b128 v[222:225], v195 offset:35840
	ds_read_b128 v[226:229], v195 offset:36864
	ds_read_b128 v[230:233], v195 offset:37888
	ds_read_b128 v[234:237], v195 offset:38912
	global_load_lds_dwordx4 v162, s[0:1]
	s_mov_b32 m0, s48
	ds_read_b128 v[238:241], v195 offset:39936
	global_load_lds_dwordx4 v166, s[0:1]
	s_waitcnt vmcnt(8) lgkmcnt(0)
	s_setprio 3
	s_barrier
	v_mfma_scale_f32_16x16x128_f8f6f4 v[152:155], v[0:7], v[210:217], v[152:155], v188, v188 op_sel_hi:[0,0,0]
	v_mfma_scale_f32_16x16x128_f8f6f4 v[148:151], v[8:15], v[210:217], v[148:151], v188, v188 op_sel_hi:[0,0,0]
	v_mfma_scale_f32_16x16x128_f8f6f4 v[140:143], v[0:7], v[218:225], v[140:143], v188, v188 op_sel_hi:[0,0,0]
	v_mfma_scale_f32_16x16x128_f8f6f4 v[132:135], v[8:15], v[218:225], v[132:135], v188, v188 op_sel_hi:[0,0,0]
	v_mfma_scale_f32_16x16x128_f8f6f4 v[124:127], v[0:7], v[226:233], v[124:127], v188, v188 op_sel_hi:[0,0,0]
	v_mfma_scale_f32_16x16x128_f8f6f4 v[120:123], v[8:15], v[226:233], v[120:123], v188, v188 op_sel_hi:[0,0,0]
	v_mfma_scale_f32_16x16x128_f8f6f4 v[108:111], v[0:7], v[234:241], v[108:111], v188, v188 op_sel_hi:[0,0,0]
	v_mfma_scale_f32_16x16x128_f8f6f4 v[100:103], v[8:15], v[234:241], v[100:103], v188, v188 op_sel_hi:[0,0,0]
	v_mfma_scale_f32_16x16x128_f8f6f4 v[156:159], v[16:23], v[210:217], v[156:159], v188, v188 op_sel_hi:[0,0,0]
	v_mfma_scale_f32_16x16x128_f8f6f4 v[144:147], v[24:31], v[210:217], v[144:147], v188, v188 op_sel_hi:[0,0,0]
	v_mfma_scale_f32_16x16x128_f8f6f4 v[136:139], v[16:23], v[218:225], v[136:139], v188, v188 op_sel_hi:[0,0,0]
	v_mfma_scale_f32_16x16x128_f8f6f4 v[128:131], v[24:31], v[218:225], v[128:131], v188, v188 op_sel_hi:[0,0,0]
	v_mfma_scale_f32_16x16x128_f8f6f4 v[116:119], v[16:23], v[226:233], v[116:119], v188, v188 op_sel_hi:[0,0,0]
	v_mfma_scale_f32_16x16x128_f8f6f4 v[112:115], v[24:31], v[226:233], v[112:115], v188, v188 op_sel_hi:[0,0,0]
	v_mfma_scale_f32_16x16x128_f8f6f4 v[104:107], v[16:23], v[234:241], v[104:107], v188, v188 op_sel_hi:[0,0,0]
	v_mfma_scale_f32_16x16x128_f8f6f4 v[96:99], v[24:31], v[234:241], v[96:99], v188, v188 op_sel_hi:[0,0,0]
	s_barrier
	s_setprio 0
	s_add_i32 s0, s66, s45
	s_add_u32 s100, s38, 0x80
	s_addc_u32 s101, s39, 0
	s_mov_b32 m0, s0
	ds_read_b128 v[210:213], v195 offset:49152
	ds_read_b128 v[214:217], v195 offset:50176
	ds_read_b128 v[218:221], v195 offset:51200
	ds_read_b128 v[222:225], v195 offset:52224
	global_load_lds_dwordx4 v164, s[100:101]
	s_add_i32 m0, s0, 0x2000
	s_add_u32 s0, s38, 0x80080
	s_addc_u32 s1, s39, 0
	s_add_i32 s38, s67, s45
	global_load_lds_dwordx4 v168, s[100:101]
	s_mov_b32 m0, s38
	ds_read_b128 v[238:241], v195 offset:56320
	global_load_lds_dwordx4 v164, s[0:1]
	s_add_i32 m0, s38, 0x2000
	ds_read_b128 v[234:237], v195 offset:55296
	global_load_lds_dwordx4 v168, s[0:1]
	s_add_u32 s100, s40, 0x80
	s_addc_u32 s101, s41, 0
	s_mov_b32 m0, s51
	ds_read_b128 v[230:233], v195 offset:54272
	global_load_lds_dwordx4 v162, s[100:101]
	s_mov_b32 m0, s52
	ds_read_b128 v[226:229], v195 offset:53248
	global_load_lds_dwordx4 v166, s[100:101]
	s_waitcnt vmcnt(8) lgkmcnt(0)
	s_setprio 3
	s_barrier
	v_mfma_scale_f32_16x16x128_f8f6f4 v[92:95], v[0:7], v[210:217], v[92:95], v188, v188 op_sel_hi:[0,0,0]
	v_mfma_scale_f32_16x16x128_f8f6f4 v[88:91], v[8:15], v[210:217], v[88:91], v188, v188 op_sel_hi:[0,0,0]
	v_mfma_scale_f32_16x16x128_f8f6f4 v[76:79], v[0:7], v[218:225], v[76:79], v188, v188 op_sel_hi:[0,0,0]
	v_mfma_scale_f32_16x16x128_f8f6f4 v[68:71], v[8:15], v[218:225], v[68:71], v188, v188 op_sel_hi:[0,0,0]
	v_mfma_scale_f32_16x16x128_f8f6f4 v[60:63], v[0:7], v[226:233], v[60:63], v188, v188 op_sel_hi:[0,0,0]
	v_mfma_scale_f32_16x16x128_f8f6f4 v[56:59], v[8:15], v[226:233], v[56:59], v188, v188 op_sel_hi:[0,0,0]
	v_mfma_scale_f32_16x16x128_f8f6f4 v[44:47], v[0:7], v[234:241], v[44:47], v188, v188 op_sel_hi:[0,0,0]
	v_mfma_scale_f32_16x16x128_f8f6f4 v[40:43], v[8:15], v[234:241], v[40:43], v188, v188 op_sel_hi:[0,0,0]
	v_mfma_scale_f32_16x16x128_f8f6f4 v[84:87], v[16:23], v[210:217], v[84:87], v188, v188 op_sel_hi:[0,0,0]
	v_mfma_scale_f32_16x16x128_f8f6f4 v[80:83], v[24:31], v[210:217], v[80:83], v188, v188 op_sel_hi:[0,0,0]
	v_mfma_scale_f32_16x16x128_f8f6f4 v[72:75], v[16:23], v[218:225], v[72:75], v188, v188 op_sel_hi:[0,0,0]
	v_mfma_scale_f32_16x16x128_f8f6f4 v[64:67], v[24:31], v[218:225], v[64:67], v188, v188 op_sel_hi:[0,0,0]
	v_mfma_scale_f32_16x16x128_f8f6f4 v[52:55], v[16:23], v[226:233], v[52:55], v188, v188 op_sel_hi:[0,0,0]
	v_mfma_scale_f32_16x16x128_f8f6f4 v[48:51], v[24:31], v[226:233], v[48:51], v188, v188 op_sel_hi:[0,0,0]
	v_mfma_scale_f32_16x16x128_f8f6f4 v[36:39], v[16:23], v[234:241], v[36:39], v188, v188 op_sel_hi:[0,0,0]
	v_mfma_scale_f32_16x16x128_f8f6f4 v[32:35], v[24:31], v[234:241], v[32:35], v188, v188 op_sel_hi:[0,0,0]
	s_barrier
	s_setprio 0
	s_add_u32 s36, s36, 0x100
	s_addc_u32 s37, s37, 0
	s_add_i32 s65, s65, 2
	s_add_u32 s63, s63, 0x100
	s_addc_u32 s64, s64, 0
	s_cmp_gt_u32 s65, 29
	s_cbranch_scc0 .LBB0_1833
	s_and_b64 vcc, exec, s[14:15]
	s_cbranch_vccz .LBB0_1836
	s_barrier

.LBB0_1974:
	v_add_u32_e32 v0, s65, v182
	v_add_u32_e32 v4, s66, v182
	ds_read_b128 v[24:27], v0
	ds_read_b128 v[28:31], v0 offset:1024
	ds_read_b128 v[16:19], v0 offset:2048
	ds_read_b128 v[20:23], v0 offset:3072
	ds_read_b128 v[8:11], v4
	ds_read_b128 v[12:15], v4 offset:1024
	ds_read_b128 v[0:3], v4 offset:2048
	ds_read_b128 v[4:7], v4 offset:3072
	s_add_i32 s35, s35, 2
	s_lshr_b32 s0, s35, 5
	s_mul_hi_u32 s1, s0, 0x4100000
	s_mul_i32 s0, s0, 0x4100000
	s_add_u32 s0, s46, s0
	s_addc_u32 s1, s47, s1
	s_and_b32 s37, s37, 0xf00
	s_add_u32 s0, s0, s37
	s_addc_u32 s1, s1, 0
	s_add_u32 s0, s0, 0x80080
	s_addc_u32 s1, s1, 0
	s_add_i32 m0, s43, 0xc000
	ds_read_b128 v[172:175], v184
	ds_read_b128 v[176:179], v184 offset:1024
	ds_read_b128 v[186:189], v184 offset:2048
	ds_read_b128 v[190:193], v184 offset:3072
	ds_read_b128 v[194:197], v184 offset:4096
	ds_read_b128 v[198:201], v184 offset:5120
	ds_read_b128 v[210:213], v184 offset:6144
	global_load_lds_dwordx4 v160, s[0:1]
	s_add_i32 m0, s43, 0xe000
	ds_read_b128 v[214:217], v184 offset:7168
	global_load_lds_dwordx4 v164, s[0:1]
	s_waitcnt vmcnt(8) lgkmcnt(0)
	s_setprio 3
	s_barrier
	v_mfma_scale_f32_16x16x128_f8f6f4 v[156:159], v[24:31], v[172:179], v[156:159], v180, v180 op_sel_hi:[0,0,0]
	v_mfma_scale_f32_16x16x128_f8f6f4 v[152:155], v[16:23], v[172:179], v[152:155], v180, v180 op_sel_hi:[0,0,0]
	v_mfma_scale_f32_16x16x128_f8f6f4 v[144:147], v[24:31], v[186:193], v[144:147], v180, v180 op_sel_hi:[0,0,0]
	v_mfma_scale_f32_16x16x128_f8f6f4 v[136:139], v[16:23], v[186:193], v[136:139], v180, v180 op_sel_hi:[0,0,0]
	v_mfma_scale_f32_16x16x128_f8f6f4 v[128:131], v[24:31], v[194:201], v[128:131], v180, v180 op_sel_hi:[0,0,0]
	v_mfma_scale_f32_16x16x128_f8f6f4 v[120:123], v[16:23], v[194:201], v[120:123], v180, v180 op_sel_hi:[0,0,0]
	v_mfma_scale_f32_16x16x128_f8f6f4 v[112:115], v[24:31], v[210:217], v[112:115], v180, v180 op_sel_hi:[0,0,0]
	v_mfma_scale_f32_16x16x128_f8f6f4 v[104:107], v[16:23], v[210:217], v[104:107], v180, v180 op_sel_hi:[0,0,0]
	v_mfma_scale_f32_16x16x128_f8f6f4 v[148:151], v[8:15], v[172:179], v[148:151], v180, v180 op_sel_hi:[0,0,0]
	v_mfma_scale_f32_16x16x128_f8f6f4 v[140:143], v[0:7], v[172:179], v[140:143], v180, v180 op_sel_hi:[0,0,0]
	v_mfma_scale_f32_16x16x128_f8f6f4 v[132:135], v[8:15], v[186:193], v[132:135], v180, v180 op_sel_hi:[0,0,0]
	v_mfma_scale_f32_16x16x128_f8f6f4 v[124:127], v[0:7], v[186:193], v[124:127], v180, v180 op_sel_hi:[0,0,0]
	v_mfma_scale_f32_16x16x128_f8f6f4 v[116:119], v[8:15], v[194:201], v[116:119], v180, v180 op_sel_hi:[0,0,0]
	v_mfma_scale_f32_16x16x128_f8f6f4 v[108:111], v[0:7], v[194:201], v[108:111], v180, v180 op_sel_hi:[0,0,0]
	v_mfma_scale_f32_16x16x128_f8f6f4 v[100:103], v[8:15], v[210:217], v[100:103], v180, v180 op_sel_hi:[0,0,0]
	v_mfma_scale_f32_16x16x128_f8f6f4 v[96:99], v[0:7], v[210:217], v[96:99], v180, v180 op_sel_hi:[0,0,0]
	s_barrier
	s_setprio 0
	s_add_i32 s0, s65, s58
	s_mov_b32 m0, s0
	ds_read_b128 v[186:189], v184 offset:16384
	ds_read_b128 v[190:193], v184 offset:17408
	ds_read_b128 v[194:197], v184 offset:18432
	ds_read_b128 v[198:201], v184 offset:19456
	ds_read_b128 v[210:213], v184 offset:20480
	global_load_lds_dwordx4 v162, s[52:53]
	s_add_i32 m0, s0, 0x2000
	s_add_u32 s0, s52, 0x80000
	s_addc_u32 s1, s53, 0
	s_add_i32 s37, s66, s58
	global_load_lds_dwordx4 v166, s[52:53]
	s_mov_b32 m0, s37
	s_nop 0
	global_load_lds_dwordx4 v162, s[0:1]
	s_add_i32 m0, s37, 0x2000
	ds_read_b128 v[222:225], v184 offset:23552
	global_load_lds_dwordx4 v166, s[0:1]
	s_mov_b32 m0, s43
	ds_read_b128 v[218:221], v184 offset:22528
	global_load_lds_dwordx4 v160, s[54:55]
	s_mov_b32 m0, s59
	ds_read_b128 v[214:217], v184 offset:21504
	global_load_lds_dwordx4 v164, s[54:55]
	s_waitcnt vmcnt(8) lgkmcnt(0)
	s_setprio 3
	s_barrier
	v_mfma_scale_f32_16x16x128_f8f6f4 v[92:95], v[24:31], v[186:193], v[92:95], v180, v180 op_sel_hi:[0,0,0]
	v_mfma_scale_f32_16x16x128_f8f6f4 v[88:91], v[16:23], v[186:193], v[88:91], v180, v180 op_sel_hi:[0,0,0]
	v_mfma_scale_f32_16x16x128_f8f6f4 v[80:83], v[24:31], v[194:201], v[80:83], v180, v180 op_sel_hi:[0,0,0]
	v_mfma_scale_f32_16x16x128_f8f6f4 v[72:75], v[16:23], v[194:201], v[72:75], v180, v180 op_sel_hi:[0,0,0]
	v_mfma_scale_f32_16x16x128_f8f6f4 v[64:67], v[24:31], v[210:217], v[64:67], v180, v180 op_sel_hi:[0,0,0]
	v_mfma_scale_f32_16x16x128_f8f6f4 v[56:59], v[16:23], v[210:217], v[56:59], v180, v180 op_sel_hi:[0,0,0]
	v_mfma_scale_f32_16x16x128_f8f6f4 v[48:51], v[24:31], v[218:225], v[48:51], v180, v180 op_sel_hi:[0,0,0]
	v_mfma_scale_f32_16x16x128_f8f6f4 v[40:43], v[16:23], v[218:225], v[40:43], v180, v180 op_sel_hi:[0,0,0]
	v_mfma_scale_f32_16x16x128_f8f6f4 v[84:87], v[8:15], v[186:193], v[84:87], v180, v180 op_sel_hi:[0,0,0]
	v_mfma_scale_f32_16x16x128_f8f6f4 v[76:79], v[0:7], v[186:193], v[76:79], v180, v180 op_sel_hi:[0,0,0]
	v_mfma_scale_f32_16x16x128_f8f6f4 v[68:71], v[8:15], v[194:201], v[68:71], v180, v180 op_sel_hi:[0,0,0]
	v_mfma_scale_f32_16x16x128_f8f6f4 v[60:63], v[0:7], v[194:201], v[60:63], v180, v180 op_sel_hi:[0,0,0]
	v_mfma_scale_f32_16x16x128_f8f6f4 v[52:55], v[8:15], v[210:217], v[52:55], v180, v180 op_sel_hi:[0,0,0]
	v_mfma_scale_f32_16x16x128_f8f6f4 v[44:47], v[0:7], v[210:217], v[44:47], v180, v180 op_sel_hi:[0,0,0]
	v_mfma_scale_f32_16x16x128_f8f6f4 v[36:39], v[8:15], v[218:225], v[36:39], v180, v180 op_sel_hi:[0,0,0]
	v_mfma_scale_f32_16x16x128_f8f6f4 v[32:35], v[0:7], v[218:225], v[32:35], v180, v180 op_sel_hi:[0,0,0]
	s_barrier
	s_setprio 0
	s_add_i32 s37, 0, 0x18000
	s_add_i32 s56, 0, 0x1c000
	v_add_u32_e32 v12, s37, v182
	v_add_u32_e32 v28, s56, v182
	ds_read_b128 v[0:3], v12
	ds_read_b128 v[4:7], v12 offset:1024
	ds_read_b128 v[8:11], v12 offset:2048
	ds_read_b128 v[12:15], v12 offset:3072
	ds_read_b128 v[16:19], v28
	ds_read_b128 v[20:23], v28 offset:1024
	ds_read_b128 v[24:27], v28 offset:2048
	ds_read_b128 v[28:31], v28 offset:3072
	s_add_u32 s0, s54, 0x80000
	s_addc_u32 s1, s55, 0
	s_mov_b32 m0, s60
	ds_read_b128 v[186:189], v184 offset:32768
	ds_read_b128 v[190:193], v184 offset:33792
	ds_read_b128 v[194:197], v184 offset:34816
	ds_read_b128 v[198:201], v184 offset:35840
	ds_read_b128 v[210:213], v184 offset:36864
	ds_read_b128 v[214:217], v184 offset:37888
	ds_read_b128 v[218:221], v184 offset:38912
	global_load_lds_dwordx4 v160, s[0:1]
	s_mov_b32 m0, s61
	ds_read_b128 v[222:225], v184 offset:39936
	global_load_lds_dwordx4 v164, s[0:1]
	s_waitcnt vmcnt(8) lgkmcnt(0)
	s_setprio 3
	s_barrier
	v_mfma_scale_f32_16x16x128_f8f6f4 v[156:159], v[0:7], v[186:193], v[156:159], v180, v180 op_sel_hi:[0,0,0]
	v_mfma_scale_f32_16x16x128_f8f6f4 v[152:155], v[8:15], v[186:193], v[152:155], v180, v180 op_sel_hi:[0,0,0]
	v_mfma_scale_f32_16x16x128_f8f6f4 v[144:147], v[0:7], v[194:201], v[144:147], v180, v180 op_sel_hi:[0,0,0]
	v_mfma_scale_f32_16x16x128_f8f6f4 v[136:139], v[8:15], v[194:201], v[136:139], v180, v180 op_sel_hi:[0,0,0]
	v_mfma_scale_f32_16x16x128_f8f6f4 v[128:131], v[0:7], v[210:217], v[128:131], v180, v180 op_sel_hi:[0,0,0]
	v_mfma_scale_f32_16x16x128_f8f6f4 v[120:123], v[8:15], v[210:217], v[120:123], v180, v180 op_sel_hi:[0,0,0]
	v_mfma_scale_f32_16x16x128_f8f6f4 v[112:115], v[0:7], v[218:225], v[112:115], v180, v180 op_sel_hi:[0,0,0]
	v_mfma_scale_f32_16x16x128_f8f6f4 v[104:107], v[8:15], v[218:225], v[104:107], v180, v180 op_sel_hi:[0,0,0]
	v_mfma_scale_f32_16x16x128_f8f6f4 v[148:151], v[16:23], v[186:193], v[148:151], v180, v180 op_sel_hi:[0,0,0]
	v_mfma_scale_f32_16x16x128_f8f6f4 v[140:143], v[24:31], v[186:193], v[140:143], v180, v180 op_sel_hi:[0,0,0]
	v_mfma_scale_f32_16x16x128_f8f6f4 v[132:135], v[16:23], v[194:201], v[132:135], v180, v180 op_sel_hi:[0,0,0]
	v_mfma_scale_f32_16x16x128_f8f6f4 v[124:127], v[24:31], v[194:201], v[124:127], v180, v180 op_sel_hi:[0,0,0]
	v_mfma_scale_f32_16x16x128_f8f6f4 v[116:119], v[16:23], v[210:217], v[116:119], v180, v180 op_sel_hi:[0,0,0]
	v_mfma_scale_f32_16x16x128_f8f6f4 v[108:111], v[24:31], v[210:217], v[108:111], v180, v180 op_sel_hi:[0,0,0]
	v_mfma_scale_f32_16x16x128_f8f6f4 v[100:103], v[16:23], v[218:225], v[100:103], v180, v180 op_sel_hi:[0,0,0]
	v_mfma_scale_f32_16x16x128_f8f6f4 v[96:99], v[24:31], v[218:225], v[96:99], v180, v180 op_sel_hi:[0,0,0]
	s_barrier
	s_setprio 0
	s_add_i32 s0, s37, s58
	s_add_u32 s100, s52, 0x80
	s_addc_u32 s101, s53, 0
	s_mov_b32 m0, s0
	ds_read_b128 v[186:189], v184 offset:49152
	ds_read_b128 v[190:193], v184 offset:50176
	ds_read_b128 v[194:197], v184 offset:51200
	ds_read_b128 v[198:201], v184 offset:52224
	global_load_lds_dwordx4 v162, s[100:101]
	s_add_i32 m0, s0, 0x2000
	s_add_u32 s0, s52, 0x80080
	s_addc_u32 s1, s53, 0
	s_add_i32 s37, s56, s58
	global_load_lds_dwordx4 v166, s[100:101]
	s_mov_b32 m0, s37
	ds_read_b128 v[222:225], v184 offset:56320
	global_load_lds_dwordx4 v162, s[0:1]
	s_add_i32 m0, s37, 0x2000
	ds_read_b128 v[218:221], v184 offset:55296
	global_load_lds_dwordx4 v166, s[0:1]
	s_add_u32 s100, s54, 0x80
	s_addc_u32 s101, s55, 0
	s_mov_b32 m0, s62
	ds_read_b128 v[214:217], v184 offset:54272
	global_load_lds_dwordx4 v160, s[100:101]
	s_mov_b32 m0, s63
	ds_read_b128 v[210:213], v184 offset:53248
	global_load_lds_dwordx4 v164, s[100:101]
	s_waitcnt vmcnt(8) lgkmcnt(0)
	s_setprio 3
	s_barrier
	v_mfma_scale_f32_16x16x128_f8f6f4 v[92:95], v[0:7], v[186:193], v[92:95], v180, v180 op_sel_hi:[0,0,0]
	v_mfma_scale_f32_16x16x128_f8f6f4 v[88:91], v[8:15], v[186:193], v[88:91], v180, v180 op_sel_hi:[0,0,0]
	v_mfma_scale_f32_16x16x128_f8f6f4 v[80:83], v[0:7], v[194:201], v[80:83], v180, v180 op_sel_hi:[0,0,0]
	v_mfma_scale_f32_16x16x128_f8f6f4 v[72:75], v[8:15], v[194:201], v[72:75], v180, v180 op_sel_hi:[0,0,0]
	v_mfma_scale_f32_16x16x128_f8f6f4 v[64:67], v[0:7], v[210:217], v[64:67], v180, v180 op_sel_hi:[0,0,0]
	v_mfma_scale_f32_16x16x128_f8f6f4 v[56:59], v[8:15], v[210:217], v[56:59], v180, v180 op_sel_hi:[0,0,0]
	v_mfma_scale_f32_16x16x128_f8f6f4 v[48:51], v[0:7], v[218:225], v[48:51], v180, v180 op_sel_hi:[0,0,0]
	v_mfma_scale_f32_16x16x128_f8f6f4 v[40:43], v[8:15], v[218:225], v[40:43], v180, v180 op_sel_hi:[0,0,0]
	v_mfma_scale_f32_16x16x128_f8f6f4 v[84:87], v[16:23], v[186:193], v[84:87], v180, v180 op_sel_hi:[0,0,0]
	v_mfma_scale_f32_16x16x128_f8f6f4 v[76:79], v[24:31], v[186:193], v[76:79], v180, v180 op_sel_hi:[0,0,0]
	v_mfma_scale_f32_16x16x128_f8f6f4 v[68:71], v[16:23], v[194:201], v[68:71], v180, v180 op_sel_hi:[0,0,0]
	v_mfma_scale_f32_16x16x128_f8f6f4 v[60:63], v[24:31], v[194:201], v[60:63], v180, v180 op_sel_hi:[0,0,0]
	v_mfma_scale_f32_16x16x128_f8f6f4 v[52:55], v[16:23], v[210:217], v[52:55], v180, v180 op_sel_hi:[0,0,0]
	v_mfma_scale_f32_16x16x128_f8f6f4 v[44:47], v[24:31], v[210:217], v[44:47], v180, v180 op_sel_hi:[0,0,0]
	v_mfma_scale_f32_16x16x128_f8f6f4 v[36:39], v[16:23], v[218:225], v[36:39], v180, v180 op_sel_hi:[0,0,0]
	v_mfma_scale_f32_16x16x128_f8f6f4 v[32:35], v[24:31], v[218:225], v[32:35], v180, v180 op_sel_hi:[0,0,0]
	s_barrier
	s_setprio 0
	s_cmpk_gt_u32 s35, 0x53
	s_mov_b32 s37, s6
	s_cbranch_scc1 .LBB0_1981
